# gate tiles layout B: full 128B lines per lane-octet, 8 lines per wave-instr scattered over 256B granules
# speedup vs baseline: 1.0199x; 1.0072x over previous
; __device__ __forceinline__ float bf_lo(unsigned w) { return __uint_as_float(w << 16); }
; __device__ __forceinline__ float bf_hi(unsigned w) { return __uint_as_float(w & 0xffff0000u); }
; #define RT(a, b) ((b) * __builtin_amdgcn_rcpf(a))
;     __device__ __forceinline__ void hook(f32x4 (&acc)[2][2][4][2], const Unit& u, int which, int wr, int wc, int fr, int fq) const {
;     ...
;                     for (int bj = 0; bj < 2; ++bj) { const unsigned off = off0 + (unsigned)(((ai * 4 + m) * 2 + bj) * 1024);
;                         gnv[m][bj] = *(const u32x4*)(gn_b + off); gdv[m][bj] = *(const u32x4*)(gd_b + off); }
; #pragma unroll
;                 for (int m = 0; m < 4; ++m)
; #pragma unroll
;                     for (int bj = 0; bj < 2; ++bj) { const u32x4 gn = gnv[m][bj], gd = gdv[m][bj];
;     ...
;                         f32x4 r0, r1;
;                         r0[0] = RT(bf_lo(gn.x), bf_lo(gd.x)); r0[1] = RT(bf_hi(gn.x), bf_hi(gd.x)); r0[2] = RT(bf_lo(gn.y), bf_lo(gd.y)); r0[3] = RT(bf_hi(gn.y), bf_hi(gd.y));
;                         r1[0] = RT(bf_lo(gn.z), bf_lo(gd.z)); r1[1] = RT(bf_hi(gn.z), bf_hi(gd.z)); r1[2] = RT(bf_lo(gn.w), bf_lo(gd.w)); r1[3] = RT(bf_hi(gn.w), bf_hi(gd.w));
;     ...
;                         acc[ai][bj][m][0] *= r0; acc[ai][bj][m][1] *= r1; }
.LBB0_52:
	s_andn2_b64 vcc, exec, s[66:67]
	s_cbranch_vccnz .LBB0_54
	v_mov_b32_e32 v96, v212
	s_nop 0
	v_readfirstlane_b32 s66, v96
	s_mov_b32 s66, 0
	s_cmp_eq_u32 s86, 4
	s_cselect_b32 s67, 0, 0x1000
	s_add_i32 s66, s66, s36
	s_add_i32 s67, s67, s31
	s_add_i32 s68, s67, s66
	s_ashr_i32 s69, s68, 31
	s_lshl_b64 s[66:67], s[68:69], 14
	s_add_u32 s66, s33, s66
	s_addc_u32 s67, s37, s67
	s_addk_i32 s68, 0x1000
	s_ashr_i32 s69, s68, 31
	v_lshlrev_b32_e32 v96, 4, v96
	s_lshl_b64 s[68:69], s[68:69], 14
	v_and_b32_e32 v96, 0x3f0, v96
	v_and_b32_e32 v98, 7, v212
	v_lshlrev_b32_e32 v98, 4, v98
	v_and_b32_e32 v99, 0x38, v212
	v_lshl_or_b32 v98, v99, 5, v98
	v_and_b32_e32 v99, 0x1c0, v212
	v_lshl_or_b32 v96, v99, 8, v98
	s_add_u32 s68, s33, s68
	s_addc_u32 s69, s37, s69
	global_load_dwordx4 v[232:235], v96, s[66:67]
	global_load_dwordx4 v[236:239], v96, s[68:69]
	v_add_u32_e32 v98, 0x80, v96
	global_load_dwordx4 v[184:187], v98, s[66:67]
	global_load_dwordx4 v[180:183], v98, s[68:69]
	v_add_u32_e32 v98, 0x800, v96
	global_load_dwordx4 v[176:179], v98, s[66:67]
	global_load_dwordx4 v[172:175], v98, s[68:69]
	v_add_u32_e32 v98, 0x880, v96
	global_load_dwordx4 v[168:171], v98, s[66:67]
	global_load_dwordx4 v[164:167], v98, s[68:69]
	v_add_u32_e32 v98, 0x1000, v96
	global_load_dwordx4 v[160:163], v98, s[66:67]
	global_load_dwordx4 v[156:159], v98, s[68:69]
	v_add_u32_e32 v98, 0x1080, v96
	global_load_dwordx4 v[152:155], v98, s[66:67]
	global_load_dwordx4 v[148:151], v98, s[68:69]
	v_add_u32_e32 v98, 0x1800, v96
	global_load_dwordx4 v[136:139], v98, s[66:67]
	global_load_dwordx4 v[132:135], v98, s[68:69]
	v_add_u32_e32 v98, 0x1880, v96
	global_load_dwordx4 v[140:143], v98, s[66:67]
	global_load_dwordx4 v[144:147], v98, s[68:69]
	s_waitcnt vmcnt(0)
	v_lshlrev_b32_e32 v231, 16, v233
	v_lshlrev_b32_e32 v98, 16, v232
	v_and_b32_e32 v99, 0xffff0000, v232
	v_rcp_f32_e32 v232, v231
	v_and_b32_e32 v231, 0xffff0000, v233
	v_rcp_f32_e32 v233, v231
	v_rcp_f32_e32 v98, v98
	v_rcp_f32_e32 v99, v99
	v_lshlrev_b32_e32 v240, 16, v236
	v_and_b32_e32 v241, 0xffff0000, v236
	v_lshlrev_b32_e32 v236, 16, v237
	v_and_b32_e32 v237, 0xffff0000, v237
	v_pk_mul_f32 v[232:233], v[232:233], v[236:237]
	v_pk_mul_f32 v[98:99], v[98:99], v[240:241]
	v_pk_mul_f32 v[130:131], v[130:131], v[232:233]
	v_lshlrev_b32_e32 v232, 16, v180
	v_and_b32_e32 v233, 0xffff0000, v180
	v_lshlrev_b32_e32 v180, 16, v185
	v_pk_mul_f32 v[128:129], v[128:129], v[98:99]
	v_lshlrev_b32_e32 v98, 16, v184
	v_and_b32_e32 v99, 0xffff0000, v184
	v_rcp_f32_e32 v184, v180
	v_and_b32_e32 v180, 0xffff0000, v185
	v_rcp_f32_e32 v185, v180
	v_rcp_f32_e32 v98, v98
	v_rcp_f32_e32 v99, v99
	v_lshlrev_b32_e32 v180, 16, v181
	v_and_b32_e32 v181, 0xffff0000, v181
	v_pk_mul_f32 v[180:181], v[184:185], v[180:181]
	v_pk_mul_f32 v[98:99], v[98:99], v[232:233]
	v_pk_mul_f32 v[126:127], v[126:127], v[180:181]
	v_lshlrev_b32_e32 v180, 16, v172
	v_and_b32_e32 v181, 0xffff0000, v172
	v_lshlrev_b32_e32 v172, 16, v177
	v_pk_mul_f32 v[124:125], v[124:125], v[98:99]
	v_lshlrev_b32_e32 v98, 16, v176
	v_and_b32_e32 v99, 0xffff0000, v176
	v_rcp_f32_e32 v176, v172
	v_and_b32_e32 v172, 0xffff0000, v177
	v_rcp_f32_e32 v98, v98
	v_rcp_f32_e32 v99, v99
	v_rcp_f32_e32 v177, v172
	v_lshlrev_b32_e32 v172, 16, v173
	v_and_b32_e32 v173, 0xffff0000, v173
	v_pk_mul_f32 v[98:99], v[98:99], v[180:181]
	v_pk_mul_f32 v[172:173], v[176:177], v[172:173]
	v_pk_mul_f32 v[112:113], v[112:113], v[98:99]
	v_pk_mul_f32 v[114:115], v[114:115], v[172:173]
	v_lshlrev_b32_e32 v98, 16, v168
	v_and_b32_e32 v99, 0xffff0000, v168
	v_lshlrev_b32_e32 v172, 16, v164
	v_and_b32_e32 v173, 0xffff0000, v164
	v_lshlrev_b32_e32 v164, 16, v169
	v_rcp_f32_e32 v98, v98
	v_rcp_f32_e32 v99, v99
	v_rcp_f32_e32 v168, v164
	v_and_b32_e32 v164, 0xffff0000, v169
	v_rcp_f32_e32 v169, v164
	v_pk_mul_f32 v[98:99], v[98:99], v[172:173]
	v_lshlrev_b32_e32 v164, 16, v165
	v_and_b32_e32 v165, 0xffff0000, v165
	v_pk_mul_f32 v[164:165], v[168:169], v[164:165]
	v_pk_mul_f32 v[104:105], v[104:105], v[98:99]
	v_lshlrev_b32_e32 v98, 16, v160
	v_and_b32_e32 v99, 0xffff0000, v160
	v_pk_mul_f32 v[106:107], v[106:107], v[164:165]
	v_rcp_f32_e32 v98, v98
	v_rcp_f32_e32 v99, v99
	v_lshlrev_b32_e32 v164, 16, v156
	v_and_b32_e32 v165, 0xffff0000, v156
	v_lshlrev_b32_e32 v156, 16, v161
	v_rcp_f32_e32 v160, v156
	v_and_b32_e32 v156, 0xffff0000, v161
	v_rcp_f32_e32 v161, v156
	v_pk_mul_f32 v[98:99], v[98:99], v[164:165]
	v_lshlrev_b32_e32 v156, 16, v157
	v_and_b32_e32 v157, 0xffff0000, v157
	v_pk_mul_f32 v[92:93], v[92:93], v[98:99]
	v_lshlrev_b32_e32 v98, 16, v152
	v_and_b32_e32 v99, 0xffff0000, v152
	v_pk_mul_f32 v[156:157], v[160:161], v[156:157]
	v_rcp_f32_e32 v98, v98
	v_rcp_f32_e32 v99, v99
	v_pk_mul_f32 v[94:95], v[94:95], v[156:157]
	v_lshlrev_b32_e32 v156, 16, v148
	v_and_b32_e32 v157, 0xffff0000, v148
	v_lshlrev_b32_e32 v148, 16, v153
	v_rcp_f32_e32 v152, v148
	v_and_b32_e32 v148, 0xffff0000, v153
	v_rcp_f32_e32 v153, v148
	v_pk_mul_f32 v[98:99], v[98:99], v[156:157]
	v_lshlrev_b32_e32 v148, 16, v149
	v_pk_mul_f32 v[84:85], v[84:85], v[98:99]
	v_lshlrev_b32_e32 v98, 16, v136
	v_and_b32_e32 v99, 0xffff0000, v136
	v_and_b32_e32 v149, 0xffff0000, v149
	v_rcp_f32_e32 v98, v98
	v_rcp_f32_e32 v99, v99
	v_pk_mul_f32 v[148:149], v[152:153], v[148:149]
	v_lshlrev_b32_e32 v176, 16, v178
	v_pk_mul_f32 v[86:87], v[86:87], v[148:149]
	v_lshlrev_b32_e32 v148, 16, v132
	v_and_b32_e32 v149, 0xffff0000, v132
	v_lshlrev_b32_e32 v132, 16, v137
	v_rcp_f32_e32 v136, v132
	v_and_b32_e32 v132, 0xffff0000, v137
	v_pk_mul_f32 v[98:99], v[98:99], v[148:149]
	v_rcp_f32_e32 v137, v132
	v_pk_mul_f32 v[76:77], v[76:77], v[98:99]
; __device__ __forceinline__ float bf_lo(unsigned w) { return __uint_as_float(w << 16); }
; __device__ __forceinline__ float bf_hi(unsigned w) { return __uint_as_float(w & 0xffff0000u); }
; #define RT(a, b) ((b) * __builtin_amdgcn_rcpf(a))
;     __device__ __forceinline__ void hook(f32x4 (&acc)[2][2][4][2], const Unit& u, int which, int wr, int wc, int fr, int fq) const {
;     ...
;                     for (int bj = 0; bj < 2; ++bj) { const unsigned off = off0 + (unsigned)(((ai * 4 + m) * 2 + bj) * 1024);
;                         gnv[m][bj] = *(const u32x4*)(gn_b + off); gdv[m][bj] = *(const u32x4*)(gd_b + off); }
; #pragma unroll
;                 for (int m = 0; m < 4; ++m)
; #pragma unroll
;                     for (int bj = 0; bj < 2; ++bj) { const u32x4 gn = gnv[m][bj], gd = gdv[m][bj];
;     ...
;                         f32x4 r0, r1;
;                         r0[0] = RT(bf_lo(gn.x), bf_lo(gd.x)); r0[1] = RT(bf_hi(gn.x), bf_hi(gd.x)); r0[2] = RT(bf_lo(gn.y), bf_lo(gd.y)); r0[3] = RT(bf_hi(gn.y), bf_hi(gd.y));
;                         r1[0] = RT(bf_lo(gn.z), bf_lo(gd.z)); r1[1] = RT(bf_hi(gn.z), bf_hi(gd.z)); r1[2] = RT(bf_lo(gn.w), bf_lo(gd.w)); r1[3] = RT(bf_hi(gn.w), bf_hi(gd.w));
;     ...
;                         acc[ai][bj][m][0] *= r0; acc[ai][bj][m][1] *= r1; }
	v_lshlrev_b32_e32 v98, 16, v140
	v_and_b32_e32 v99, 0xffff0000, v140
	v_and_b32_e32 v177, 0xffff0000, v178
	v_lshlrev_b32_e32 v180, 16, v174
	v_and_b32_e32 v181, 0xffff0000, v174
	v_lshlrev_b32_e32 v174, 16, v179
	v_lshlrev_b32_e32 v168, 16, v170
	v_and_b32_e32 v169, 0xffff0000, v170
	v_lshlrev_b32_e32 v172, 16, v166
	v_and_b32_e32 v173, 0xffff0000, v166
	v_lshlrev_b32_e32 v166, 16, v171
	v_rcp_f32_e32 v98, v98
	v_rcp_f32_e32 v99, v99
	v_rcp_f32_e32 v176, v176
	v_rcp_f32_e32 v177, v177
	v_rcp_f32_e32 v178, v174
	v_and_b32_e32 v174, 0xffff0000, v179
	v_rcp_f32_e32 v168, v168
	v_rcp_f32_e32 v169, v169
	v_rcp_f32_e32 v170, v166
	v_and_b32_e32 v166, 0xffff0000, v171
	v_lshlrev_b32_e32 v132, 16, v133
	v_and_b32_e32 v133, 0xffff0000, v133
	v_rcp_f32_e32 v179, v174
	v_rcp_f32_e32 v171, v166
	v_pk_mul_f32 v[132:133], v[136:137], v[132:133]
	v_lshlrev_b32_e32 v232, 16, v182
	v_pk_mul_f32 v[78:79], v[78:79], v[132:133]
	v_lshlrev_b32_e32 v132, 16, v144
	v_and_b32_e32 v133, 0xffff0000, v144
	v_pk_mul_f32 v[98:99], v[98:99], v[132:133]
	v_and_b32_e32 v233, 0xffff0000, v182
	v_lshlrev_b32_e32 v182, 16, v187
	v_pk_mul_f32 v[176:177], v[176:177], v[180:181]
	v_lshlrev_b32_e32 v174, 16, v175
	v_and_b32_e32 v175, 0xffff0000, v175
	v_pk_mul_f32 v[168:169], v[168:169], v[172:173]
	v_lshlrev_b32_e32 v166, 16, v167
	v_and_b32_e32 v167, 0xffff0000, v167
	v_pk_mul_f32 v[68:69], v[68:69], v[98:99]
	v_add_u32_e32 v98, 0x2000, v96
	v_lshlrev_b32_e32 v184, 16, v186
	v_and_b32_e32 v185, 0xffff0000, v186
	v_rcp_f32_e32 v186, v182
	v_and_b32_e32 v182, 0xffff0000, v187
	v_pk_mul_f32 v[174:175], v[178:179], v[174:175]
	v_pk_mul_f32 v[108:109], v[108:109], v[176:177]
	v_pk_mul_f32 v[166:167], v[170:171], v[166:167]
	v_pk_mul_f32 v[100:101], v[100:101], v[168:169]
	global_load_dwordx4 v[168:171], v98, s[66:67]
	global_load_dwordx4 v[176:179], v98, s[68:69]
	v_rcp_f32_e32 v184, v184
	v_rcp_f32_e32 v185, v185
	v_rcp_f32_e32 v187, v182
	v_lshlrev_b32_e32 v231, 16, v234
	v_lshlrev_b32_e32 v182, 16, v183
	v_and_b32_e32 v183, 0xffff0000, v183
	v_rcp_f32_e32 v236, v231
	v_and_b32_e32 v231, 0xffff0000, v234
	v_pk_mul_f32 v[184:185], v[184:185], v[232:233]
	v_pk_mul_f32 v[182:183], v[186:187], v[182:183]
	v_add_u32_e32 v98, 0x2080, v96
	v_rcp_f32_e32 v237, v231
	v_lshlrev_b32_e32 v231, 16, v235
	v_pk_mul_f32 v[118:119], v[118:119], v[182:183]
	v_pk_mul_f32 v[116:117], v[116:117], v[184:185]
	global_load_dwordx4 v[180:183], v98, s[66:67]
	global_load_dwordx4 v[184:187], v98, s[68:69]
	v_rcp_f32_e32 v234, v231
	v_and_b32_e32 v231, 0xffff0000, v235
	v_rcp_f32_e32 v235, v231
	v_lshlrev_b32_e32 v240, 16, v238
	v_and_b32_e32 v241, 0xffff0000, v238
	v_lshlrev_b32_e32 v238, 16, v239
	v_and_b32_e32 v239, 0xffff0000, v239
	v_pk_mul_f32 v[236:237], v[236:237], v[240:241]
	v_pk_mul_f32 v[234:235], v[234:235], v[238:239]
	v_add_u32_e32 v98, 0x2800, v96
	v_pk_mul_f32 v[122:123], v[122:123], v[234:235]
	v_pk_mul_f32 v[120:121], v[120:121], v[236:237]
	global_load_dwordx4 v[232:235], v98, s[66:67]
	global_load_dwordx4 v[236:239], v98, s[68:69]
	v_lshlrev_b32_e32 v160, 16, v162
	v_and_b32_e32 v161, 0xffff0000, v162
	v_rcp_f32_e32 v160, v160
	v_rcp_f32_e32 v161, v161
	v_lshlrev_b32_e32 v164, 16, v158
	v_and_b32_e32 v165, 0xffff0000, v158
	v_add_u32_e32 v98, 0x2880, v96
	v_pk_mul_f32 v[110:111], v[110:111], v[174:175]
	v_pk_mul_f32 v[102:103], v[102:103], v[166:167]
	v_pk_mul_f32 v[160:161], v[160:161], v[164:165]
	global_load_dwordx4 v[172:175], v98, s[66:67]
	global_load_dwordx4 v[164:167], v98, s[68:69]
	v_lshlrev_b32_e32 v158, 16, v163
	v_rcp_f32_e32 v162, v158
	v_and_b32_e32 v158, 0xffff0000, v163
	v_rcp_f32_e32 v163, v158
	v_lshlrev_b32_e32 v152, 16, v154
	v_and_b32_e32 v153, 0xffff0000, v154
	v_rcp_f32_e32 v152, v152
	v_rcp_f32_e32 v153, v153
	v_lshlrev_b32_e32 v158, 16, v159
	v_and_b32_e32 v159, 0xffff0000, v159
	v_pk_mul_f32 v[158:159], v[162:163], v[158:159]
	v_lshlrev_b32_e32 v156, 16, v150
	v_and_b32_e32 v157, 0xffff0000, v150
	v_add_u32_e32 v98, 0x3000, v96
	v_pk_mul_f32 v[90:91], v[90:91], v[158:159]
	v_pk_mul_f32 v[88:89], v[88:89], v[160:161]
	v_pk_mul_f32 v[152:153], v[152:153], v[156:157]
	v_lshlrev_b32_e32 v150, 16, v155
	global_load_dwordx4 v[160:163], v98, s[66:67]
	global_load_dwordx4 v[156:159], v98, s[68:69]
	v_rcp_f32_e32 v154, v150
	v_and_b32_e32 v150, 0xffff0000, v155
	v_lshlrev_b32_e32 v148, 16, v134
	v_and_b32_e32 v149, 0xffff0000, v134
	v_lshlrev_b32_e32 v134, 16, v139
	v_rcp_f32_e32 v155, v150
	v_lshlrev_b32_e32 v136, 16, v138
	v_and_b32_e32 v137, 0xffff0000, v138
	v_rcp_f32_e32 v138, v134
	v_and_b32_e32 v134, 0xffff0000, v139
	v_rcp_f32_e32 v136, v136
	v_rcp_f32_e32 v137, v137
	v_rcp_f32_e32 v139, v134
	v_lshlrev_b32_e32 v132, 16, v141
	v_and_b32_e32 v133, 0xffff0000, v141
	v_lshlrev_b32_e32 v150, 16, v151
	v_and_b32_e32 v151, 0xffff0000, v151
	v_rcp_f32_e32 v132, v132
	v_rcp_f32_e32 v133, v133
	v_pk_mul_f32 v[150:151], v[154:155], v[150:151]
	v_lshlrev_b32_e32 v134, 16, v135
	v_and_b32_e32 v135, 0xffff0000, v135
	v_add_u32_e32 v98, 0x3080, v96
	v_pk_mul_f32 v[82:83], v[82:83], v[150:151]
	v_pk_mul_f32 v[80:81], v[80:81], v[152:153]
	v_pk_mul_f32 v[136:137], v[136:137], v[148:149]
	v_pk_mul_f32 v[134:135], v[138:139], v[134:135]
	global_load_dwordx4 v[152:155], v98, s[66:67]
	global_load_dwordx4 v[148:151], v98, s[68:69]
	v_pk_mul_f32 v[74:75], v[74:75], v[134:135]
	v_lshlrev_b32_e32 v134, 16, v145
	v_and_b32_e32 v135, 0xffff0000, v145
	v_pk_mul_f32 v[132:133], v[132:133], v[134:135]
	v_lshlrev_b32_e32 v134, 16, v142
	v_and_b32_e32 v135, 0xffff0000, v142
	v_rcp_f32_e32 v134, v134
	v_rcp_f32_e32 v135, v135
	v_pk_mul_f32 v[72:73], v[72:73], v[136:137]
	v_lshlrev_b32_e32 v136, 16, v146
	v_and_b32_e32 v137, 0xffff0000, v146
	v_add_u32_e32 v98, 0x3800, v96
	v_pk_mul_f32 v[134:135], v[134:135], v[136:137]
	v_lshlrev_b32_e32 v136, 16, v143
	v_and_b32_e32 v137, 0xffff0000, v143
	v_lshlrev_b32_e32 v138, 16, v147
	v_and_b32_e32 v139, 0xffff0000, v147
	global_load_dwordx4 v[144:147], v98, s[66:67]
	global_load_dwordx4 v[140:143], v98, s[68:69]
	v_rcp_f32_e32 v136, v136
	v_rcp_f32_e32 v137, v137
	v_add_u32_e32 v98, 0x3880, v96
	v_pk_mul_f32 v[70:71], v[70:71], v[132:133]
	v_pk_mul_f32 v[64:65], v[64:65], v[134:135]
	v_pk_mul_f32 v[136:137], v[136:137], v[138:139]
	s_waitcnt vmcnt(0)
; __device__ __forceinline__ float bf_lo(unsigned w) { return __uint_as_float(w << 16); }
; __device__ __forceinline__ float bf_hi(unsigned w) { return __uint_as_float(w & 0xffff0000u); }
; #define RT(a, b) ((b) * __builtin_amdgcn_rcpf(a))
;     __device__ __forceinline__ void hook(f32x4 (&acc)[2][2][4][2], const Unit& u, int which, int wr, int wc, int fr, int fq) const {
;     ...
;                     for (int bj = 0; bj < 2; ++bj) { const u32x4 gn = gnv[m][bj], gd = gdv[m][bj];
;     ...
;                         f32x4 r0, r1;
;                         r0[0] = RT(bf_lo(gn.x), bf_lo(gd.x)); r0[1] = RT(bf_hi(gn.x), bf_hi(gd.x)); r0[2] = RT(bf_lo(gn.y), bf_lo(gd.y)); r0[3] = RT(bf_hi(gn.y), bf_hi(gd.y));
;                         r1[0] = RT(bf_lo(gn.z), bf_lo(gd.z)); r1[1] = RT(bf_hi(gn.z), bf_hi(gd.z)); r1[2] = RT(bf_lo(gn.w), bf_lo(gd.w)); r1[3] = RT(bf_hi(gn.w), bf_hi(gd.w));
;     ...
;                         acc[ai][bj][m][0] *= r0; acc[ai][bj][m][1] *= r1; }
	v_and_b32_e32 v99, 0xffff0000, v168
	v_pk_mul_f32 v[66:67], v[66:67], v[136:137]
	global_load_dwordx4 v[136:139], v98, s[66:67]
	global_load_dwordx4 v[132:135], v98, s[68:69]
	v_lshlrev_b32_e32 v98, 16, v168
	v_rcp_f32_e32 v98, v98
	v_rcp_f32_e32 v99, v99
	v_lshlrev_b32_e32 v168, 16, v169
	v_and_b32_e32 v169, 0xffff0000, v169
	v_lshlrev_b32_e32 v240, 16, v176
	v_and_b32_e32 v241, 0xffff0000, v176
	v_rcp_f32_e32 v168, v168
	v_rcp_f32_e32 v169, v169
	v_pk_mul_f32 v[98:99], v[98:99], v[240:241]
	v_lshlrev_b32_e32 v176, 16, v177
	v_pk_mul_f32 v[60:61], v[60:61], v[98:99]
	v_lshlrev_b32_e32 v98, 16, v180
	v_and_b32_e32 v99, 0xffff0000, v180
	v_and_b32_e32 v177, 0xffff0000, v177
	v_rcp_f32_e32 v98, v98
	v_rcp_f32_e32 v99, v99
	v_pk_mul_f32 v[168:169], v[168:169], v[176:177]
	v_lshlrev_b32_e32 v176, 16, v170
	v_and_b32_e32 v170, 0xffff0000, v170
	v_rcp_f32_e32 v177, v170
	v_lshlrev_b32_e32 v170, 16, v171
	v_and_b32_e32 v171, 0xffff0000, v171
	v_rcp_f32_e32 v170, v170
	v_rcp_f32_e32 v171, v171
	v_pk_mul_f32 v[62:63], v[62:63], v[168:169]
	v_lshlrev_b32_e32 v168, 16, v184
	v_and_b32_e32 v169, 0xffff0000, v184
	v_pk_mul_f32 v[98:99], v[98:99], v[168:169]
	v_lshlrev_b32_e32 v168, 16, v181
	v_and_b32_e32 v169, 0xffff0000, v181
	v_rcp_f32_e32 v168, v168
	v_rcp_f32_e32 v169, v169
	v_lshlrev_b32_e32 v240, 16, v178
	v_and_b32_e32 v241, 0xffff0000, v178
	v_lshlrev_b32_e32 v178, 16, v179
	v_and_b32_e32 v179, 0xffff0000, v179
	v_pk_mul_f32 v[52:53], v[52:53], v[98:99]
	v_lshlrev_b32_e32 v98, 16, v232
	v_and_b32_e32 v99, 0xffff0000, v232
	v_pk_mul_f32 v[170:171], v[170:171], v[178:179]
	v_rcp_f32_e32 v98, v98
	v_rcp_f32_e32 v99, v99
	v_rcp_f32_e32 v176, v176
	v_pk_mul_f32 v[58:59], v[58:59], v[170:171]
	v_lshlrev_b32_e32 v170, 16, v185
	v_and_b32_e32 v171, 0xffff0000, v185
	v_pk_mul_f32 v[168:169], v[168:169], v[170:171]
	v_lshlrev_b32_e32 v170, 16, v182
	v_and_b32_e32 v171, 0xffff0000, v182
	v_rcp_f32_e32 v170, v170
	v_rcp_f32_e32 v171, v171
	v_pk_mul_f32 v[54:55], v[54:55], v[168:169]
	v_lshlrev_b32_e32 v168, 16, v236
	v_and_b32_e32 v169, 0xffff0000, v236
	v_pk_mul_f32 v[98:99], v[98:99], v[168:169]
	v_lshlrev_b32_e32 v168, 16, v233
	v_and_b32_e32 v169, 0xffff0000, v233
	v_pk_mul_f32 v[176:177], v[176:177], v[240:241]
	v_rcp_f32_e32 v168, v168
	v_rcp_f32_e32 v169, v169
	v_pk_mul_f32 v[56:57], v[56:57], v[176:177]
	v_lshlrev_b32_e32 v176, 16, v186
	v_and_b32_e32 v177, 0xffff0000, v186
	v_pk_mul_f32 v[44:45], v[44:45], v[98:99]
	v_lshlrev_b32_e32 v98, 16, v172
	v_and_b32_e32 v99, 0xffff0000, v172
	v_pk_mul_f32 v[170:171], v[170:171], v[176:177]
	v_rcp_f32_e32 v98, v98
	v_rcp_f32_e32 v99, v99
	v_pk_mul_f32 v[48:49], v[48:49], v[170:171]
	v_lshlrev_b32_e32 v170, 16, v237
	v_and_b32_e32 v171, 0xffff0000, v237
	v_pk_mul_f32 v[168:169], v[168:169], v[170:171]
	v_lshlrev_b32_e32 v176, 16, v183
	v_pk_mul_f32 v[46:47], v[46:47], v[168:169]
	v_lshlrev_b32_e32 v168, 16, v164
	v_and_b32_e32 v169, 0xffff0000, v164
	v_lshlrev_b32_e32 v164, 16, v173
	v_pk_mul_f32 v[98:99], v[98:99], v[168:169]
	v_rcp_f32_e32 v168, v164
	v_and_b32_e32 v164, 0xffff0000, v173
	v_rcp_f32_e32 v169, v164
	v_lshlrev_b32_e32 v164, 16, v165
	v_and_b32_e32 v165, 0xffff0000, v165
	v_pk_mul_f32 v[36:37], v[36:37], v[98:99]
	v_pk_mul_f32 v[164:165], v[168:169], v[164:165]
	v_lshlrev_b32_e32 v98, 16, v160
	v_pk_mul_f32 v[38:39], v[38:39], v[164:165]
	v_lshlrev_b32_e32 v164, 16, v156
	v_and_b32_e32 v165, 0xffff0000, v156
	v_lshlrev_b32_e32 v156, 16, v161
	v_and_b32_e32 v99, 0xffff0000, v160
	v_rcp_f32_e32 v160, v156
	v_and_b32_e32 v156, 0xffff0000, v161
	v_rcp_f32_e32 v161, v156
	v_rcp_f32_e32 v98, v98
	v_rcp_f32_e32 v99, v99
	v_lshlrev_b32_e32 v156, 16, v157
	v_and_b32_e32 v157, 0xffff0000, v157
	v_pk_mul_f32 v[156:157], v[160:161], v[156:157]
	v_pk_mul_f32 v[98:99], v[98:99], v[164:165]
	v_pk_mul_f32 v[30:31], v[30:31], v[156:157]
	v_lshlrev_b32_e32 v156, 16, v148
	v_and_b32_e32 v157, 0xffff0000, v148
	v_lshlrev_b32_e32 v148, 16, v153
	v_pk_mul_f32 v[28:29], v[28:29], v[98:99]
	v_lshlrev_b32_e32 v98, 16, v152
	v_and_b32_e32 v99, 0xffff0000, v152
	v_rcp_f32_e32 v152, v148
	v_and_b32_e32 v148, 0xffff0000, v153
	v_rcp_f32_e32 v153, v148
	v_rcp_f32_e32 v98, v98
	v_rcp_f32_e32 v99, v99
	v_lshlrev_b32_e32 v148, 16, v149
	v_and_b32_e32 v149, 0xffff0000, v149
	v_pk_mul_f32 v[148:149], v[152:153], v[148:149]
	v_pk_mul_f32 v[98:99], v[98:99], v[156:157]
	v_pk_mul_f32 v[22:23], v[22:23], v[148:149]
	v_lshlrev_b32_e32 v148, 16, v140
	v_and_b32_e32 v149, 0xffff0000, v140
	v_lshlrev_b32_e32 v140, 16, v145
	v_pk_mul_f32 v[20:21], v[20:21], v[98:99]
	v_lshlrev_b32_e32 v98, 16, v144
	v_and_b32_e32 v99, 0xffff0000, v144
	v_rcp_f32_e32 v144, v140
	v_and_b32_e32 v140, 0xffff0000, v145
	v_rcp_f32_e32 v98, v98
	v_rcp_f32_e32 v99, v99
	v_rcp_f32_e32 v145, v140
	v_and_b32_e32 v177, 0xffff0000, v183
	v_rcp_f32_e32 v176, v176
	v_rcp_f32_e32 v177, v177
	v_lshlrev_b32_e32 v140, 16, v141
	v_and_b32_e32 v141, 0xffff0000, v141
	v_lshlrev_b32_e32 v170, 16, v234
	v_and_b32_e32 v171, 0xffff0000, v234
	v_pk_mul_f32 v[98:99], v[98:99], v[148:149]
	v_pk_mul_f32 v[140:141], v[144:145], v[140:141]
	v_rcp_f32_e32 v170, v170
	v_rcp_f32_e32 v171, v171
	v_pk_mul_f32 v[18:19], v[18:19], v[140:141]
	v_pk_mul_f32 v[16:17], v[16:17], v[98:99]
	s_waitcnt vmcnt(0)
; __device__ __forceinline__ float bf_lo(unsigned w) { return __uint_as_float(w << 16); }
; __device__ __forceinline__ float bf_hi(unsigned w) { return __uint_as_float(w & 0xffff0000u); }
; #define RT(a, b) ((b) * __builtin_amdgcn_rcpf(a))
;     __device__ __forceinline__ void hook(f32x4 (&acc)[2][2][4][2], const Unit& u, int which, int wr, int wc, int fr, int fq) const {
;     ...
;                     for (int bj = 0; bj < 2; ++bj) { const u32x4 gn = gnv[m][bj], gd = gdv[m][bj];
;     ...
;                         f32x4 r0, r1;
;                         r0[0] = RT(bf_lo(gn.x), bf_lo(gd.x)); r0[1] = RT(bf_hi(gn.x), bf_hi(gd.x)); r0[2] = RT(bf_lo(gn.y), bf_lo(gd.y)); r0[3] = RT(bf_hi(gn.y), bf_hi(gd.y));
;                         r1[0] = RT(bf_lo(gn.z), bf_lo(gd.z)); r1[1] = RT(bf_hi(gn.z), bf_hi(gd.z)); r1[2] = RT(bf_lo(gn.w), bf_lo(gd.w)); r1[3] = RT(bf_hi(gn.w), bf_hi(gd.w));
;     ...
;                         acc[ai][bj][m][0] *= r0; acc[ai][bj][m][1] *= r1; }
	v_lshlrev_b32_e32 v98, 16, v136
	v_and_b32_e32 v99, 0xffff0000, v136
	v_lshlrev_b32_e32 v140, 16, v132
	v_and_b32_e32 v141, 0xffff0000, v132
	v_lshlrev_b32_e32 v132, 16, v137
	v_lshlrev_b32_e32 v178, 16, v187
	v_and_b32_e32 v179, 0xffff0000, v187
	v_lshlrev_b32_e32 v168, 16, v174
	v_and_b32_e32 v169, 0xffff0000, v174
	v_rcp_f32_e32 v98, v98
	v_rcp_f32_e32 v99, v99
	v_rcp_f32_e32 v136, v132
	v_and_b32_e32 v132, 0xffff0000, v137
	v_pk_mul_f32 v[176:177], v[176:177], v[178:179]
	v_rcp_f32_e32 v168, v168
	v_rcp_f32_e32 v169, v169
	v_rcp_f32_e32 v137, v132
	v_pk_mul_f32 v[50:51], v[50:51], v[176:177]
	v_lshlrev_b32_e32 v176, 16, v238
	v_and_b32_e32 v177, 0xffff0000, v238
	v_pk_mul_f32 v[170:171], v[170:171], v[176:177]
	v_lshlrev_b32_e32 v164, 16, v158
	v_pk_mul_f32 v[40:41], v[40:41], v[170:171]
	v_lshlrev_b32_e32 v170, 16, v166
	v_and_b32_e32 v171, 0xffff0000, v166
	v_lshlrev_b32_e32 v166, 16, v175
	v_and_b32_e32 v165, 0xffff0000, v158
	v_lshlrev_b32_e32 v158, 16, v163
	v_lshlrev_b32_e32 v156, 16, v150
	v_and_b32_e32 v157, 0xffff0000, v150
	v_lshlrev_b32_e32 v150, 16, v155
	v_lshlrev_b32_e32 v148, 16, v142
	v_and_b32_e32 v149, 0xffff0000, v142
	v_lshlrev_b32_e32 v142, 16, v147
	v_pk_mul_f32 v[98:99], v[98:99], v[140:141]
	v_lshlrev_b32_e32 v132, 16, v133
	v_and_b32_e32 v133, 0xffff0000, v133
	v_lshlrev_b32_e32 v140, 16, v134
	v_and_b32_e32 v141, 0xffff0000, v134
	v_lshlrev_b32_e32 v134, 16, v139
	v_lshlrev_b32_e32 v176, 16, v235
	v_and_b32_e32 v177, 0xffff0000, v235
	v_pk_mul_f32 v[168:169], v[168:169], v[170:171]
	v_rcp_f32_e32 v170, v166
	v_and_b32_e32 v166, 0xffff0000, v175
	v_lshlrev_b32_e32 v160, 16, v162
	v_and_b32_e32 v161, 0xffff0000, v162
	v_rcp_f32_e32 v162, v158
	v_and_b32_e32 v158, 0xffff0000, v163
	v_lshlrev_b32_e32 v152, 16, v154
	v_and_b32_e32 v153, 0xffff0000, v154
	v_rcp_f32_e32 v154, v150
	v_and_b32_e32 v150, 0xffff0000, v155
	v_lshlrev_b32_e32 v144, 16, v146
	v_and_b32_e32 v145, 0xffff0000, v146
	v_rcp_f32_e32 v146, v142
	v_and_b32_e32 v142, 0xffff0000, v147
	v_pk_mul_f32 v[132:133], v[136:137], v[132:133]
	v_lshlrev_b32_e32 v136, 16, v138
	v_and_b32_e32 v137, 0xffff0000, v138
	v_rcp_f32_e32 v138, v134
	v_and_b32_e32 v134, 0xffff0000, v139
	v_rcp_f32_e32 v176, v176
	v_rcp_f32_e32 v177, v177
	v_rcp_f32_e32 v171, v166
	v_rcp_f32_e32 v160, v160
	v_rcp_f32_e32 v161, v161
	v_rcp_f32_e32 v163, v158
	v_rcp_f32_e32 v152, v152
	v_rcp_f32_e32 v153, v153
	v_rcp_f32_e32 v155, v150
	v_rcp_f32_e32 v144, v144
	v_rcp_f32_e32 v145, v145
	v_rcp_f32_e32 v147, v142
	v_rcp_f32_e32 v136, v136
	v_rcp_f32_e32 v137, v137
	v_rcp_f32_e32 v139, v134
	v_lshlrev_b32_e32 v178, 16, v239
	v_and_b32_e32 v179, 0xffff0000, v239
	v_lshlrev_b32_e32 v166, 16, v167
	v_and_b32_e32 v167, 0xffff0000, v167
	v_lshlrev_b32_e32 v158, 16, v159
	v_and_b32_e32 v159, 0xffff0000, v159
	v_lshlrev_b32_e32 v150, 16, v151
	v_and_b32_e32 v151, 0xffff0000, v151
	v_lshlrev_b32_e32 v142, 16, v143
	v_and_b32_e32 v143, 0xffff0000, v143
	v_lshlrev_b32_e32 v134, 16, v135
	v_and_b32_e32 v135, 0xffff0000, v135
	v_pk_mul_f32 v[176:177], v[176:177], v[178:179]
	v_pk_mul_f32 v[166:167], v[170:171], v[166:167]
	v_pk_mul_f32 v[160:161], v[160:161], v[164:165]
	v_pk_mul_f32 v[158:159], v[162:163], v[158:159]
	v_pk_mul_f32 v[152:153], v[152:153], v[156:157]
	v_pk_mul_f32 v[150:151], v[154:155], v[150:151]
	v_pk_mul_f32 v[144:145], v[144:145], v[148:149]
	v_pk_mul_f32 v[142:143], v[146:147], v[142:143]
	v_pk_mul_f32 v[136:137], v[136:137], v[140:141]
	v_pk_mul_f32 v[134:135], v[138:139], v[134:135]
	v_pk_mul_f32 v[42:43], v[42:43], v[176:177]
	v_pk_mul_f32 v[34:35], v[34:35], v[166:167]
	v_pk_mul_f32 v[32:33], v[32:33], v[168:169]
	v_pk_mul_f32 v[26:27], v[26:27], v[158:159]
	v_pk_mul_f32 v[24:25], v[24:25], v[160:161]
	v_pk_mul_f32 v[14:15], v[14:15], v[150:151]
	v_pk_mul_f32 v[12:13], v[12:13], v[152:153]
	v_pk_mul_f32 v[10:11], v[10:11], v[142:143]
	v_pk_mul_f32 v[8:9], v[8:9], v[144:145]
	v_pk_mul_f32 v[6:7], v[6:7], v[132:133]
	v_pk_mul_f32 v[4:5], v[4:5], v[98:99]
	v_pk_mul_f32 v[2:3], v[2:3], v[134:135]
	v_pk_mul_f32 v[0:1], v[0:1], v[136:137]

; __device__ __forceinline__ float bf_lo(unsigned w) { return __uint_as_float(w << 16); }
; __device__ __forceinline__ float bf_hi(unsigned w) { return __uint_as_float(w & 0xffff0000u); }
; __device__ __forceinline__ unsigned cvt_pk_bf16(float lo, float hi) { f32x2_t v = {lo, hi}; bf16x2_t b = __builtin_convertvector(v, bf16x2_t); return __builtin_bit_cast(unsigned, b); }
; #define EPI_LANE() int t__ = threadIdx.x; asm volatile("" : "+v"(t__)); const int wid__ = __builtin_amdgcn_readfirstlane(t__ >> 6); wr = wid__ >> 2; wc = wid__ & 3; fr = t__ & 15; fq = (t__ & 63) >> 4
;     __device__ __forceinline__ void operator()(const f32x4 (&acc)[2][2][4][2], const Unit& u, int wr, int wc, int fr, int fq) const {
;         EPI_LANE();
;         const char* g_b = gbase(2, u, wid__) + (t__ & 63) * 16; char* mb = (char*)(Mg + (size_t)u.pm * BM * 1024 + u.pn * BM);
;         unsigned rl0 = (unsigned)(wr * 64 + fr), cl0 = (unsigned)(wc * 32 + 8 * fq); asm volatile("" : "+v"(rl0), "+v"(cl0));
; #pragma unroll
;         for (int ai = 0; ai < 2; ++ai) {
;             u32x4 gv[4][2];
; #pragma unroll
;             for (int m = 0; m < 4; ++m)
; #pragma unroll
;                 for (int bj = 0; bj < 2; ++bj) gv[m][bj] = *(const u32x4*)(g_b + ((ai * 4 + m) * 2 + bj) * 1024);
; #pragma unroll
;             for (int m = 0; m < 4; ++m) { const unsigned rl = rl0 + (unsigned)(ai * HALF + m * 16);
; #pragma unroll
;                 for (int bj = 0; bj < 2; ++bj) { const unsigned cl = cl0 + (unsigned)(bj * HALF);
;                     const u32x4 g = gv[m][bj];
;                     const f32x4 v0 = acc[ai][bj][m][0], v1 = acc[ai][bj][m][1];
;                     u32x4 w;
;                     w.x = cvt_pk_bf16(v0[0] * __builtin_amdgcn_rcpf(bf_lo(g.x)), v0[1] * __builtin_amdgcn_rcpf(bf_hi(g.x)));
;                     w.y = cvt_pk_bf16(v0[2] * __builtin_amdgcn_rcpf(bf_lo(g.y)), v0[3] * __builtin_amdgcn_rcpf(bf_hi(g.y)));
;                     w.z = cvt_pk_bf16(v1[0] * __builtin_amdgcn_rcpf(bf_lo(g.z)), v1[1] * __builtin_amdgcn_rcpf(bf_hi(g.z)));
;                     w.w = cvt_pk_bf16(v1[2] * __builtin_amdgcn_rcpf(bf_lo(g.w)), v1[3] * __builtin_amdgcn_rcpf(bf_hi(g.w)));
;                     *(u32x4*)(mb + (rl * 1024u + cl) * 2u) = w; } }
.LBB0_57:
	v_mov_b32_e32 v132, v212
	s_lshl_b32 s61, s6, 10
	v_readfirstlane_b32 s31, v132
	s_lshl_b32 s62, s60, 3
	s_ashr_i32 s36, s31, 6
	s_add_i32 s61, s61, s62
	s_nop 0
	s_add_i32 s62, s61, 0x2000
	s_ashr_i32 s63, s62, 31
	s_lshl_b64 s[62:63], s[62:63], 14
	s_add_u32 s62, s33, s62
	s_addc_u32 s63, s37, s63
	s_ashr_i32 s61, s60, 31
	s_lshl_b64 s[60:61], s[60:61], 19
	s_add_u32 s64, s89, s60
	s_addc_u32 s65, s3, s61
	s_lshl_b32 s60, s6, 8
	s_ashr_i32 s61, s60, 31
	s_lshl_b64 s[60:61], s[60:61], 1
	s_add_u32 s60, s64, s60
	s_addc_u32 s61, s65, s61
	s_ashr_i32 s6, s31, 2
	s_andn2_b32 s6, s6, 63
	v_and_or_b32 v158, v132, 15, s6
	s_lshl_b32 s6, s36, 5
	v_lshlrev_b32_e32 v96, 4, v132
	s_and_b32 s6, s6, 0x60
	v_lshrrev_b32_e32 v132, 1, v132
	v_and_b32_e32 v96, 0x3f0, v96
	v_and_b32_e32 v171, 7, v212
	v_lshlrev_b32_e32 v171, 4, v171
	v_and_b32_e32 v172, 0x38, v212
	v_lshl_or_b32 v171, v172, 5, v171
	v_and_b32_e32 v172, 0x1c0, v212
	v_lshl_or_b32 v170, v172, 8, v171
	v_and_or_b32 v159, v132, 24, s6
	v_mov_b32_e32 v171, v170
	global_load_dwordx4 v[160:163], v171, s[62:63]
	v_add_u32_e32 v171, 0x80, v170
	global_load_dwordx4 v[164:167], v171, s[62:63]
	v_add_u32_e32 v171, 0x800, v170
	global_load_dwordx4 v[152:155], v171, s[62:63]
	v_add_u32_e32 v171, 0x880, v170
	global_load_dwordx4 v[148:151], v171, s[62:63]
	v_lshl_add_u64 v[98:99], s[62:63], 0, v[96:97]
	s_movk_i32 s6, 0x1000
	v_add_co_u32_e32 v132, vcc, s6, v98
	s_movk_i32 s6, 0x2000
	s_nop 0
	v_addc_co_u32_e32 v133, vcc, 0, v99, vcc
	v_add_co_u32_e32 v156, vcc, s6, v98
	v_lshlrev_b32_e32 v96, 1, v159
	s_nop 0
	v_addc_co_u32_e32 v157, vcc, 0, v99, vcc
	v_add_u32_e32 v171, 0x1000, v170
	global_load_dwordx4 v[144:147], v171, s[62:63]
	v_add_u32_e32 v171, 0x1080, v170
	global_load_dwordx4 v[140:143], v171, s[62:63]
	v_add_u32_e32 v171, 0x1800, v170
	global_load_dwordx4 v[136:139], v171, s[62:63]
	s_nop 0
	v_add_u32_e32 v171, 0x1880, v170
	global_load_dwordx4 v[132:135], v171, s[62:63]
	v_lshl_add_u32 v96, v158, 11, v96
	s_movk_i32 s6, 0x3000
	s_waitcnt vmcnt(0)
	v_lshlrev_b32_e32 v168, 16, v160
	v_and_b32_e32 v160, 0xffff0000, v160
	v_rcp_f32_e32 v168, v168
	v_rcp_f32_e32 v169, v160
	s_nop 0
	v_pk_mul_f32 v[128:129], v[128:129], v[168:169]
	s_nop 0
	v_cvt_pk_bf16_f32 v128, v128, v129
	v_lshlrev_b32_e32 v129, 16, v161
	v_rcp_f32_e32 v160, v129
	v_and_b32_e32 v129, 0xffff0000, v161
	v_rcp_f32_e32 v161, v129
	s_nop 0
	v_pk_mul_f32 v[130:131], v[130:131], v[160:161]
	s_nop 0
	v_cvt_pk_bf16_f32 v129, v130, v131
	v_lshlrev_b32_e32 v130, 16, v162
	v_and_b32_e32 v131, 0xffff0000, v162
	v_rcp_f32_e32 v130, v130
	v_rcp_f32_e32 v131, v131
	s_nop 0
	v_pk_mul_f32 v[120:121], v[120:121], v[130:131]
	s_nop 0
	v_cvt_pk_bf16_f32 v130, v120, v121
	v_lshlrev_b32_e32 v120, 16, v163
	v_and_b32_e32 v121, 0xffff0000, v163
	v_rcp_f32_e32 v120, v120
	v_rcp_f32_e32 v121, v121
	s_nop 0
	v_pk_mul_f32 v[120:121], v[122:123], v[120:121]
	s_nop 0
	v_cvt_pk_bf16_f32 v131, v120, v121
	v_lshlrev_b32_e32 v120, 16, v164
	v_and_b32_e32 v121, 0xffff0000, v164
	v_rcp_f32_e32 v120, v120
	v_rcp_f32_e32 v121, v121
	global_store_dwordx4 v96, v[128:131], s[60:61]
	v_pk_mul_f32 v[120:121], v[124:125], v[120:121]
	s_nop 0
	v_cvt_pk_bf16_f32 v120, v120, v121
	v_lshlrev_b32_e32 v121, 16, v165
	v_rcp_f32_e32 v122, v121
	v_and_b32_e32 v121, 0xffff0000, v165
	v_rcp_f32_e32 v123, v121
	s_nop 0
	v_pk_mul_f32 v[122:123], v[126:127], v[122:123]
	s_nop 0
	v_cvt_pk_bf16_f32 v121, v122, v123
	v_lshlrev_b32_e32 v122, 16, v166
	v_and_b32_e32 v123, 0xffff0000, v166
	v_rcp_f32_e32 v122, v122
	v_rcp_f32_e32 v123, v123
	s_nop 0
	v_pk_mul_f32 v[116:117], v[116:117], v[122:123]
	s_nop 0
	v_cvt_pk_bf16_f32 v122, v116, v117
	v_lshlrev_b32_e32 v116, 16, v167
	v_and_b32_e32 v117, 0xffff0000, v167
	v_rcp_f32_e32 v116, v116
	v_rcp_f32_e32 v117, v117
	s_nop 0
	v_pk_mul_f32 v[116:117], v[118:119], v[116:117]
	s_nop 0
	v_cvt_pk_bf16_f32 v123, v116, v117
	v_add_u32_e32 v116, 0x100, v96
	global_store_dwordx4 v116, v[120:123], s[60:61]
	v_lshlrev_b32_e32 v116, 16, v152
	v_and_b32_e32 v117, 0xffff0000, v152
	v_rcp_f32_e32 v116, v116
	v_rcp_f32_e32 v117, v117
	v_add_u32_e32 v118, 0x8000, v96
	v_pk_mul_f32 v[112:113], v[112:113], v[116:117]
	s_nop 0
	v_cvt_pk_bf16_f32 v112, v112, v113
	v_lshlrev_b32_e32 v113, 16, v153
	v_rcp_f32_e32 v116, v113
	v_and_b32_e32 v113, 0xffff0000, v153
	v_rcp_f32_e32 v117, v113
	s_nop 0
	v_pk_mul_f32 v[114:115], v[114:115], v[116:117]
	s_nop 0
	v_cvt_pk_bf16_f32 v113, v114, v115
	v_lshlrev_b32_e32 v114, 16, v154
	v_and_b32_e32 v115, 0xffff0000, v154
	v_rcp_f32_e32 v114, v114
	v_rcp_f32_e32 v115, v115
	s_nop 0
	v_pk_mul_f32 v[108:109], v[108:109], v[114:115]
	s_nop 0
	v_cvt_pk_bf16_f32 v114, v108, v109
	v_lshlrev_b32_e32 v108, 16, v155
	v_and_b32_e32 v109, 0xffff0000, v155
	v_rcp_f32_e32 v108, v108
	v_rcp_f32_e32 v109, v109
	s_nop 0
	v_pk_mul_f32 v[108:109], v[110:111], v[108:109]
	s_nop 0
	v_cvt_pk_bf16_f32 v115, v108, v109
	v_lshlrev_b32_e32 v108, 16, v148
	v_and_b32_e32 v109, 0xffff0000, v148
	v_rcp_f32_e32 v108, v108
	v_rcp_f32_e32 v109, v109
	global_store_dwordx4 v118, v[112:115], s[60:61]
	v_pk_mul_f32 v[104:105], v[104:105], v[108:109]
	s_nop 0
	v_cvt_pk_bf16_f32 v104, v104, v105
	v_lshlrev_b32_e32 v105, 16, v149
	v_rcp_f32_e32 v108, v105
	v_and_b32_e32 v105, 0xffff0000, v149
	v_rcp_f32_e32 v109, v105
	s_nop 0
	v_pk_mul_f32 v[106:107], v[106:107], v[108:109]
	s_nop 0
	v_cvt_pk_bf16_f32 v105, v106, v107
	v_lshlrev_b32_e32 v106, 16, v150
	v_and_b32_e32 v107, 0xffff0000, v150
	v_rcp_f32_e32 v106, v106
	v_rcp_f32_e32 v107, v107
	s_nop 0
	v_pk_mul_f32 v[100:101], v[100:101], v[106:107]
	s_nop 0
	v_cvt_pk_bf16_f32 v106, v100, v101
; __device__ __forceinline__ float bf_lo(unsigned w) { return __uint_as_float(w << 16); }
; __device__ __forceinline__ float bf_hi(unsigned w) { return __uint_as_float(w & 0xffff0000u); }
; __device__ __forceinline__ unsigned cvt_pk_bf16(float lo, float hi) { f32x2_t v = {lo, hi}; bf16x2_t b = __builtin_convertvector(v, bf16x2_t); return __builtin_bit_cast(unsigned, b); }
;     __device__ __forceinline__ void operator()(const f32x4 (&acc)[2][2][4][2], const Unit& u, int wr, int wc, int fr, int fq) const {
;     ...
;                 for (int bj = 0; bj < 2; ++bj) gv[m][bj] = *(const u32x4*)(g_b + ((ai * 4 + m) * 2 + bj) * 1024);
; #pragma unroll
;             for (int m = 0; m < 4; ++m) { const unsigned rl = rl0 + (unsigned)(ai * HALF + m * 16);
; #pragma unroll
;                 for (int bj = 0; bj < 2; ++bj) { const unsigned cl = cl0 + (unsigned)(bj * HALF);
;                     const u32x4 g = gv[m][bj];
;                     const f32x4 v0 = acc[ai][bj][m][0], v1 = acc[ai][bj][m][1];
;                     u32x4 w;
;                     w.x = cvt_pk_bf16(v0[0] * __builtin_amdgcn_rcpf(bf_lo(g.x)), v0[1] * __builtin_amdgcn_rcpf(bf_hi(g.x)));
;                     w.y = cvt_pk_bf16(v0[2] * __builtin_amdgcn_rcpf(bf_lo(g.y)), v0[3] * __builtin_amdgcn_rcpf(bf_hi(g.y)));
;                     w.z = cvt_pk_bf16(v1[0] * __builtin_amdgcn_rcpf(bf_lo(g.z)), v1[1] * __builtin_amdgcn_rcpf(bf_hi(g.z)));
;                     w.w = cvt_pk_bf16(v1[2] * __builtin_amdgcn_rcpf(bf_lo(g.w)), v1[3] * __builtin_amdgcn_rcpf(bf_hi(g.w)));
;                     *(u32x4*)(mb + (rl * 1024u + cl) * 2u) = w; } }
	v_lshlrev_b32_e32 v100, 16, v151
	v_and_b32_e32 v101, 0xffff0000, v151
	v_rcp_f32_e32 v100, v100
	v_rcp_f32_e32 v101, v101
	s_nop 0
	v_pk_mul_f32 v[100:101], v[102:103], v[100:101]
	s_nop 0
	v_cvt_pk_bf16_f32 v107, v100, v101
	v_add_u32_e32 v100, 0x8100, v96
	global_store_dwordx4 v100, v[104:107], s[60:61]
	v_lshlrev_b32_e32 v100, 16, v144
	v_and_b32_e32 v101, 0xffff0000, v144
	v_rcp_f32_e32 v100, v100
	v_rcp_f32_e32 v101, v101
	v_add_u32_e32 v102, 0x10000, v96
	v_pk_mul_f32 v[92:93], v[92:93], v[100:101]
	s_nop 0
	v_cvt_pk_bf16_f32 v92, v92, v93
	v_lshlrev_b32_e32 v93, 16, v145
	v_rcp_f32_e32 v100, v93
	v_and_b32_e32 v93, 0xffff0000, v145
	v_rcp_f32_e32 v101, v93
	s_nop 0
	v_pk_mul_f32 v[94:95], v[94:95], v[100:101]
	s_nop 0
	v_cvt_pk_bf16_f32 v93, v94, v95
	v_lshlrev_b32_e32 v94, 16, v146
	v_and_b32_e32 v95, 0xffff0000, v146
	v_rcp_f32_e32 v94, v94
	v_rcp_f32_e32 v95, v95
	s_nop 0
	v_pk_mul_f32 v[88:89], v[88:89], v[94:95]
	s_nop 0
	v_cvt_pk_bf16_f32 v94, v88, v89
	v_lshlrev_b32_e32 v88, 16, v147
	v_and_b32_e32 v89, 0xffff0000, v147
	v_rcp_f32_e32 v88, v88
	v_rcp_f32_e32 v89, v89
	s_nop 0
	v_pk_mul_f32 v[88:89], v[90:91], v[88:89]
	s_nop 0
	v_cvt_pk_bf16_f32 v95, v88, v89
	v_lshlrev_b32_e32 v88, 16, v140
	v_and_b32_e32 v89, 0xffff0000, v140
	v_rcp_f32_e32 v88, v88
	v_rcp_f32_e32 v89, v89
	global_store_dwordx4 v102, v[92:95], s[60:61]
	v_pk_mul_f32 v[84:85], v[84:85], v[88:89]
	s_nop 0
	v_cvt_pk_bf16_f32 v84, v84, v85
	v_lshlrev_b32_e32 v85, 16, v141
	v_rcp_f32_e32 v88, v85
	v_and_b32_e32 v85, 0xffff0000, v141
	v_rcp_f32_e32 v89, v85
	s_nop 0
	v_pk_mul_f32 v[86:87], v[86:87], v[88:89]
	s_nop 0
	v_cvt_pk_bf16_f32 v85, v86, v87
	v_lshlrev_b32_e32 v86, 16, v142
	v_and_b32_e32 v87, 0xffff0000, v142
	v_rcp_f32_e32 v86, v86
	v_rcp_f32_e32 v87, v87
	s_nop 0
	v_pk_mul_f32 v[80:81], v[80:81], v[86:87]
	s_nop 0
	v_cvt_pk_bf16_f32 v86, v80, v81
	v_lshlrev_b32_e32 v80, 16, v143
	v_and_b32_e32 v81, 0xffff0000, v143
	v_rcp_f32_e32 v80, v80
	v_rcp_f32_e32 v81, v81
	s_nop 0
	v_pk_mul_f32 v[80:81], v[82:83], v[80:81]
	s_nop 0
	v_cvt_pk_bf16_f32 v87, v80, v81
	v_add_u32_e32 v80, 0x10100, v96
	global_store_dwordx4 v80, v[84:87], s[60:61]
	v_lshlrev_b32_e32 v80, 16, v136
	v_and_b32_e32 v81, 0xffff0000, v136
	v_rcp_f32_e32 v80, v80
	v_rcp_f32_e32 v81, v81
	v_add_u32_e32 v82, 0x18000, v96
	v_pk_mul_f32 v[76:77], v[76:77], v[80:81]
	s_nop 0
	v_cvt_pk_bf16_f32 v76, v76, v77
	v_lshlrev_b32_e32 v77, 16, v137
	v_rcp_f32_e32 v80, v77
	v_and_b32_e32 v77, 0xffff0000, v137
	v_rcp_f32_e32 v81, v77
	s_nop 0
	v_pk_mul_f32 v[78:79], v[78:79], v[80:81]
	s_nop 0
	v_cvt_pk_bf16_f32 v77, v78, v79
	v_lshlrev_b32_e32 v78, 16, v138
	v_and_b32_e32 v79, 0xffff0000, v138
	v_rcp_f32_e32 v78, v78
	v_rcp_f32_e32 v79, v79
	s_nop 0
	v_pk_mul_f32 v[72:73], v[72:73], v[78:79]
	s_nop 0
	v_cvt_pk_bf16_f32 v78, v72, v73
	v_lshlrev_b32_e32 v72, 16, v139
	v_and_b32_e32 v73, 0xffff0000, v139
	v_rcp_f32_e32 v72, v72
	v_rcp_f32_e32 v73, v73
	s_nop 0
	v_pk_mul_f32 v[72:73], v[74:75], v[72:73]
	s_nop 0
	v_cvt_pk_bf16_f32 v79, v72, v73
	v_lshlrev_b32_e32 v72, 16, v132
	v_and_b32_e32 v73, 0xffff0000, v132
	v_rcp_f32_e32 v72, v72
	v_rcp_f32_e32 v73, v73
	global_store_dwordx4 v82, v[76:79], s[60:61]
	v_pk_mul_f32 v[68:69], v[68:69], v[72:73]
	s_nop 0
	v_cvt_pk_bf16_f32 v68, v68, v69
	v_lshlrev_b32_e32 v69, 16, v133
	v_rcp_f32_e32 v72, v69
	v_and_b32_e32 v69, 0xffff0000, v133
	v_rcp_f32_e32 v73, v69
	s_nop 0
	v_pk_mul_f32 v[70:71], v[70:71], v[72:73]
	s_nop 0
	v_cvt_pk_bf16_f32 v69, v70, v71
	v_lshlrev_b32_e32 v70, 16, v134
	v_and_b32_e32 v71, 0xffff0000, v134
	v_rcp_f32_e32 v70, v70
	v_rcp_f32_e32 v71, v71
	s_nop 0
	v_pk_mul_f32 v[64:65], v[64:65], v[70:71]
	s_nop 0
	v_cvt_pk_bf16_f32 v70, v64, v65
	v_lshlrev_b32_e32 v64, 16, v135
	v_and_b32_e32 v65, 0xffff0000, v135
	v_rcp_f32_e32 v64, v64
	v_rcp_f32_e32 v65, v65
	s_nop 0
	v_pk_mul_f32 v[64:65], v[66:67], v[64:65]
	s_nop 0
	v_cvt_pk_bf16_f32 v71, v64, v65
	v_add_u32_e32 v64, 0x18100, v96
	global_store_dwordx4 v64, v[68:71], s[60:61]
	v_add_u32_e32 v171, 0x2000, v170
	global_load_dwordx4 v[90:93], v171, s[62:63]
	v_add_u32_e32 v171, 0x2080, v170
	global_load_dwordx4 v[100:103], v171, s[62:63]
	v_add_u32_e32 v171, 0x2800, v170
	global_load_dwordx4 v[84:87], v171, s[62:63]
	v_add_u32_e32 v171, 0x2880, v170
	global_load_dwordx4 v[80:83], v171, s[62:63]
	v_add_co_u32_e32 v64, vcc, s6, v98
	v_lshlrev_b32_e32 v88, 11, v158
	s_nop 0
	v_addc_co_u32_e32 v65, vcc, 0, v99, vcc
	v_add_u32_e32 v171, 0x3000, v170
	global_load_dwordx4 v[76:79], v171, s[62:63]
	v_add_u32_e32 v171, 0x3080, v170
	global_load_dwordx4 v[72:75], v171, s[62:63]
	v_add_u32_e32 v171, 0x3800, v170
	global_load_dwordx4 v[68:71], v171, s[62:63]
	s_nop 0
	v_add_u32_e32 v171, 0x3880, v170
	global_load_dwordx4 v[64:67], v171, s[62:63]
	v_lshl_add_u32 v88, v159, 1, v88
	v_add_u32_e32 v89, 0x40000, v88
	s_and_b64 vcc, exec, s[38:39]
	s_waitcnt vmcnt(0)
; __device__ __forceinline__ float bf_lo(unsigned w) { return __uint_as_float(w << 16); }
; __device__ __forceinline__ float bf_hi(unsigned w) { return __uint_as_float(w & 0xffff0000u); }
; __device__ __forceinline__ unsigned cvt_pk_bf16(float lo, float hi) { f32x2_t v = {lo, hi}; bf16x2_t b = __builtin_convertvector(v, bf16x2_t); return __builtin_bit_cast(unsigned, b); }
;     __device__ __forceinline__ void operator()(const f32x4 (&acc)[2][2][4][2], const Unit& u, int wr, int wc, int fr, int fq) const {
;     ...
;             for (int m = 0; m < 4; ++m) { const unsigned rl = rl0 + (unsigned)(ai * HALF + m * 16);
; #pragma unroll
;                 for (int bj = 0; bj < 2; ++bj) { const unsigned cl = cl0 + (unsigned)(bj * HALF);
;                     const u32x4 g = gv[m][bj];
;                     const f32x4 v0 = acc[ai][bj][m][0], v1 = acc[ai][bj][m][1];
;                     u32x4 w;
;                     w.x = cvt_pk_bf16(v0[0] * __builtin_amdgcn_rcpf(bf_lo(g.x)), v0[1] * __builtin_amdgcn_rcpf(bf_hi(g.x)));
;                     w.y = cvt_pk_bf16(v0[2] * __builtin_amdgcn_rcpf(bf_lo(g.y)), v0[3] * __builtin_amdgcn_rcpf(bf_hi(g.y)));
;                     w.z = cvt_pk_bf16(v1[0] * __builtin_amdgcn_rcpf(bf_lo(g.z)), v1[1] * __builtin_amdgcn_rcpf(bf_hi(g.z)));
;                     w.w = cvt_pk_bf16(v1[2] * __builtin_amdgcn_rcpf(bf_lo(g.w)), v1[3] * __builtin_amdgcn_rcpf(bf_hi(g.w)));
;                     *(u32x4*)(mb + (rl * 1024u + cl) * 2u) = w; } }
	v_lshlrev_b32_e32 v94, 16, v90
	v_and_b32_e32 v90, 0xffff0000, v90
	v_rcp_f32_e32 v94, v94
	v_rcp_f32_e32 v95, v90
	s_nop 0
	v_pk_mul_f32 v[60:61], v[60:61], v[94:95]
	s_nop 0
	v_cvt_pk_bf16_f32 v60, v60, v61
	v_lshlrev_b32_e32 v61, 16, v91
	v_rcp_f32_e32 v90, v61
	v_and_b32_e32 v61, 0xffff0000, v91
	v_rcp_f32_e32 v91, v61
	s_nop 0
	v_pk_mul_f32 v[62:63], v[62:63], v[90:91]
	s_nop 0
	v_cvt_pk_bf16_f32 v61, v62, v63
	v_lshlrev_b32_e32 v62, 16, v92
	v_and_b32_e32 v63, 0xffff0000, v92
	v_rcp_f32_e32 v62, v62
	v_rcp_f32_e32 v63, v63
	s_nop 0
	v_pk_mul_f32 v[56:57], v[56:57], v[62:63]
	s_nop 0
	v_cvt_pk_bf16_f32 v62, v56, v57
	v_lshlrev_b32_e32 v56, 16, v93
	v_and_b32_e32 v57, 0xffff0000, v93
	v_rcp_f32_e32 v56, v56
	v_rcp_f32_e32 v57, v57
	s_nop 0
	v_pk_mul_f32 v[56:57], v[58:59], v[56:57]
	s_nop 0
	v_cvt_pk_bf16_f32 v63, v56, v57
	v_lshlrev_b32_e32 v56, 16, v100
	v_and_b32_e32 v57, 0xffff0000, v100
	v_rcp_f32_e32 v56, v56
	v_rcp_f32_e32 v57, v57
	global_store_dwordx4 v89, v[60:63], s[60:61]
	v_pk_mul_f32 v[52:53], v[52:53], v[56:57]
	s_nop 0
	v_cvt_pk_bf16_f32 v52, v52, v53
	v_lshlrev_b32_e32 v53, 16, v101
	v_rcp_f32_e32 v56, v53
	v_and_b32_e32 v53, 0xffff0000, v101
	v_rcp_f32_e32 v57, v53
	s_nop 0
	v_pk_mul_f32 v[54:55], v[54:55], v[56:57]
	s_nop 0
	v_cvt_pk_bf16_f32 v53, v54, v55
	v_lshlrev_b32_e32 v54, 16, v102
	v_and_b32_e32 v55, 0xffff0000, v102
	v_rcp_f32_e32 v54, v54
	v_rcp_f32_e32 v55, v55
	s_nop 0
	v_pk_mul_f32 v[48:49], v[48:49], v[54:55]
	s_nop 0
	v_cvt_pk_bf16_f32 v54, v48, v49
	v_lshlrev_b32_e32 v48, 16, v103
	v_and_b32_e32 v49, 0xffff0000, v103
	v_rcp_f32_e32 v48, v48
	v_rcp_f32_e32 v49, v49
	s_nop 0
	v_pk_mul_f32 v[48:49], v[50:51], v[48:49]
	s_nop 0
	v_cvt_pk_bf16_f32 v55, v48, v49
	v_add_u32_e32 v48, 0x40100, v88
	global_store_dwordx4 v48, v[52:55], s[60:61]
	v_lshlrev_b32_e32 v48, 16, v84
	v_and_b32_e32 v49, 0xffff0000, v84
	v_rcp_f32_e32 v48, v48
	v_rcp_f32_e32 v49, v49
	v_add_u32_e32 v50, 0x48000, v88
	v_pk_mul_f32 v[44:45], v[44:45], v[48:49]
	s_nop 0
	v_cvt_pk_bf16_f32 v44, v44, v45
	v_lshlrev_b32_e32 v45, 16, v85
	v_rcp_f32_e32 v48, v45
	v_and_b32_e32 v45, 0xffff0000, v85
	v_rcp_f32_e32 v49, v45
	s_nop 0
	v_pk_mul_f32 v[46:47], v[46:47], v[48:49]
	s_nop 0
	v_cvt_pk_bf16_f32 v45, v46, v47
	v_lshlrev_b32_e32 v46, 16, v86
	v_and_b32_e32 v47, 0xffff0000, v86
	v_rcp_f32_e32 v46, v46
	v_rcp_f32_e32 v47, v47
	s_nop 0
	v_pk_mul_f32 v[40:41], v[40:41], v[46:47]
	s_nop 0
	v_cvt_pk_bf16_f32 v46, v40, v41
	v_lshlrev_b32_e32 v40, 16, v87
	v_and_b32_e32 v41, 0xffff0000, v87
	v_rcp_f32_e32 v40, v40
	v_rcp_f32_e32 v41, v41
	s_nop 0
	v_pk_mul_f32 v[40:41], v[42:43], v[40:41]
	s_nop 0
	v_cvt_pk_bf16_f32 v47, v40, v41
	v_lshlrev_b32_e32 v40, 16, v80
	v_and_b32_e32 v41, 0xffff0000, v80
	v_rcp_f32_e32 v40, v40
	v_rcp_f32_e32 v41, v41
	global_store_dwordx4 v50, v[44:47], s[60:61]
	v_pk_mul_f32 v[36:37], v[36:37], v[40:41]
	s_nop 0
	v_cvt_pk_bf16_f32 v36, v36, v37
	v_lshlrev_b32_e32 v37, 16, v81
	v_rcp_f32_e32 v40, v37
	v_and_b32_e32 v37, 0xffff0000, v81
	v_rcp_f32_e32 v41, v37
	s_nop 0
	v_pk_mul_f32 v[38:39], v[38:39], v[40:41]
	s_nop 0
	v_cvt_pk_bf16_f32 v37, v38, v39
	v_lshlrev_b32_e32 v38, 16, v82
	v_and_b32_e32 v39, 0xffff0000, v82
	v_rcp_f32_e32 v38, v38
	v_rcp_f32_e32 v39, v39
	s_nop 0
	v_pk_mul_f32 v[32:33], v[32:33], v[38:39]
	s_nop 0
	v_cvt_pk_bf16_f32 v38, v32, v33
	v_lshlrev_b32_e32 v32, 16, v83
	v_and_b32_e32 v33, 0xffff0000, v83
	v_rcp_f32_e32 v32, v32
	v_rcp_f32_e32 v33, v33
	s_nop 0
	v_pk_mul_f32 v[32:33], v[34:35], v[32:33]
	s_nop 0
	v_cvt_pk_bf16_f32 v39, v32, v33
	v_add_u32_e32 v32, 0x48100, v88
	global_store_dwordx4 v32, v[36:39], s[60:61]
	v_lshlrev_b32_e32 v32, 16, v76
; __device__ __forceinline__ float bf_lo(unsigned w) { return __uint_as_float(w << 16); }
; __device__ __forceinline__ float bf_hi(unsigned w) { return __uint_as_float(w & 0xffff0000u); }
; __device__ __forceinline__ unsigned cvt_pk_bf16(float lo, float hi) { f32x2_t v = {lo, hi}; bf16x2_t b = __builtin_convertvector(v, bf16x2_t); return __builtin_bit_cast(unsigned, b); }
;     __device__ __forceinline__ void operator()(const f32x4 (&acc)[2][2][4][2], const Unit& u, int wr, int wc, int fr, int fq) const {
;     ...
;             for (int m = 0; m < 4; ++m) { const unsigned rl = rl0 + (unsigned)(ai * HALF + m * 16);
; #pragma unroll
;                 for (int bj = 0; bj < 2; ++bj) { const unsigned cl = cl0 + (unsigned)(bj * HALF);
;                     const u32x4 g = gv[m][bj];
;                     const f32x4 v0 = acc[ai][bj][m][0], v1 = acc[ai][bj][m][1];
;                     u32x4 w;
;                     w.x = cvt_pk_bf16(v0[0] * __builtin_amdgcn_rcpf(bf_lo(g.x)), v0[1] * __builtin_amdgcn_rcpf(bf_hi(g.x)));
;                     w.y = cvt_pk_bf16(v0[2] * __builtin_amdgcn_rcpf(bf_lo(g.y)), v0[3] * __builtin_amdgcn_rcpf(bf_hi(g.y)));
;                     w.z = cvt_pk_bf16(v1[0] * __builtin_amdgcn_rcpf(bf_lo(g.z)), v1[1] * __builtin_amdgcn_rcpf(bf_hi(g.z)));
;                     w.w = cvt_pk_bf16(v1[2] * __builtin_amdgcn_rcpf(bf_lo(g.w)), v1[3] * __builtin_amdgcn_rcpf(bf_hi(g.w)));
;                     *(u32x4*)(mb + (rl * 1024u + cl) * 2u) = w; } }
;             asm volatile("" : "+v"(rl0), "+v"(cl0) :: "memory"); }
	v_and_b32_e32 v33, 0xffff0000, v76
	v_rcp_f32_e32 v32, v32
	v_rcp_f32_e32 v33, v33
	v_add_u32_e32 v34, 0x50000, v88
	v_pk_mul_f32 v[28:29], v[28:29], v[32:33]
	s_nop 0
	v_cvt_pk_bf16_f32 v28, v28, v29
	v_lshlrev_b32_e32 v29, 16, v77
	v_rcp_f32_e32 v32, v29
	v_and_b32_e32 v29, 0xffff0000, v77
	v_rcp_f32_e32 v33, v29
	s_nop 0
	v_pk_mul_f32 v[30:31], v[30:31], v[32:33]
	s_nop 0
	v_cvt_pk_bf16_f32 v29, v30, v31
	v_lshlrev_b32_e32 v30, 16, v78
	v_and_b32_e32 v31, 0xffff0000, v78
	v_rcp_f32_e32 v30, v30
	v_rcp_f32_e32 v31, v31
	s_nop 0
	v_pk_mul_f32 v[24:25], v[24:25], v[30:31]
	s_nop 0
	v_cvt_pk_bf16_f32 v30, v24, v25
	v_lshlrev_b32_e32 v24, 16, v79
	v_and_b32_e32 v25, 0xffff0000, v79
	v_rcp_f32_e32 v24, v24
	v_rcp_f32_e32 v25, v25
	s_nop 0
	v_pk_mul_f32 v[24:25], v[26:27], v[24:25]
	s_nop 0
	v_cvt_pk_bf16_f32 v31, v24, v25
	v_lshlrev_b32_e32 v24, 16, v72
	v_and_b32_e32 v25, 0xffff0000, v72
	v_rcp_f32_e32 v24, v24
	v_rcp_f32_e32 v25, v25
	global_store_dwordx4 v34, v[28:31], s[60:61]
	v_pk_mul_f32 v[20:21], v[20:21], v[24:25]
	s_nop 0
	v_cvt_pk_bf16_f32 v20, v20, v21
	v_lshlrev_b32_e32 v21, 16, v73
	v_rcp_f32_e32 v24, v21
	v_and_b32_e32 v21, 0xffff0000, v73
	v_rcp_f32_e32 v25, v21
	s_nop 0
	v_pk_mul_f32 v[22:23], v[22:23], v[24:25]
	s_nop 0
	v_cvt_pk_bf16_f32 v21, v22, v23
	v_lshlrev_b32_e32 v22, 16, v74
	v_and_b32_e32 v23, 0xffff0000, v74
	v_rcp_f32_e32 v22, v22
	v_rcp_f32_e32 v23, v23
	s_nop 0
	v_pk_mul_f32 v[12:13], v[12:13], v[22:23]
	s_nop 0
	v_cvt_pk_bf16_f32 v22, v12, v13
	v_lshlrev_b32_e32 v12, 16, v75
	v_and_b32_e32 v13, 0xffff0000, v75
	v_rcp_f32_e32 v12, v12
	v_rcp_f32_e32 v13, v13
	s_nop 0
	v_pk_mul_f32 v[12:13], v[14:15], v[12:13]
	s_nop 0
	v_cvt_pk_bf16_f32 v23, v12, v13
	v_add_u32_e32 v12, 0x50100, v88
	global_store_dwordx4 v12, v[20:23], s[60:61]
	v_lshlrev_b32_e32 v12, 16, v68
	v_and_b32_e32 v13, 0xffff0000, v68
	v_rcp_f32_e32 v12, v12
	v_rcp_f32_e32 v13, v13
	v_add_u32_e32 v20, 0x58000, v88
	v_pk_mul_f32 v[12:13], v[16:17], v[12:13]
	s_nop 0
	v_cvt_pk_bf16_f32 v12, v12, v13
	v_lshlrev_b32_e32 v13, 16, v69
	v_rcp_f32_e32 v14, v13
	v_and_b32_e32 v13, 0xffff0000, v69
	v_rcp_f32_e32 v15, v13
	s_nop 0
	v_pk_mul_f32 v[14:15], v[18:19], v[14:15]
	s_nop 0
	v_cvt_pk_bf16_f32 v13, v14, v15
	v_lshlrev_b32_e32 v14, 16, v70
	v_and_b32_e32 v15, 0xffff0000, v70
	v_rcp_f32_e32 v14, v14
	v_rcp_f32_e32 v15, v15
	s_nop 0
	v_pk_mul_f32 v[8:9], v[8:9], v[14:15]
	s_nop 0
	v_cvt_pk_bf16_f32 v14, v8, v9
	v_lshlrev_b32_e32 v8, 16, v71
	v_and_b32_e32 v9, 0xffff0000, v71
	v_rcp_f32_e32 v8, v8
	v_rcp_f32_e32 v9, v9
	s_nop 0
	v_pk_mul_f32 v[8:9], v[10:11], v[8:9]
	s_nop 0
	v_cvt_pk_bf16_f32 v15, v8, v9
	v_lshlrev_b32_e32 v8, 16, v64
	v_and_b32_e32 v9, 0xffff0000, v64
	v_rcp_f32_e32 v8, v8
	v_rcp_f32_e32 v9, v9
	global_store_dwordx4 v20, v[12:15], s[60:61]
	v_pk_mul_f32 v[4:5], v[4:5], v[8:9]
	s_nop 0
	v_cvt_pk_bf16_f32 v4, v4, v5
	v_lshlrev_b32_e32 v5, 16, v65
	v_rcp_f32_e32 v8, v5
	v_and_b32_e32 v5, 0xffff0000, v65
	v_rcp_f32_e32 v9, v5
	s_nop 0
	v_pk_mul_f32 v[6:7], v[6:7], v[8:9]
	s_nop 0
	v_cvt_pk_bf16_f32 v5, v6, v7
	v_lshlrev_b32_e32 v6, 16, v66
	v_and_b32_e32 v7, 0xffff0000, v66
	v_rcp_f32_e32 v6, v6
	v_rcp_f32_e32 v7, v7
	s_nop 0
	v_pk_mul_f32 v[0:1], v[0:1], v[6:7]
	s_nop 0
	v_cvt_pk_bf16_f32 v6, v0, v1
	v_lshlrev_b32_e32 v0, 16, v67
	v_and_b32_e32 v1, 0xffff0000, v67
	v_rcp_f32_e32 v0, v0
	v_rcp_f32_e32 v1, v1
	s_nop 0
	v_pk_mul_f32 v[0:1], v[2:3], v[0:1]
	s_nop 0
	v_cvt_pk_bf16_f32 v7, v0, v1
	v_add_u32_e32 v0, 0x58100, v88
	global_store_dwordx4 v0, v[4:7], s[60:61]
	s_mov_b64 s[60:61], -1
	s_cbranch_vccnz .LBB0_35
	s_andn2_b64 vcc, exec, s[46:47]
	s_cbranch_vccnz .LBB0_34
	s_barrier
	s_branch .LBB0_34

; __device__ __forceinline__ unsigned cvt_pk_bf16(float lo, float hi) { f32x2_t v = {lo, hi}; bf16x2_t b = __builtin_convertvector(v, bf16x2_t); return __builtin_bit_cast(unsigned, b); }
; template <int MODE> __device__ __forceinline__ float actf(float v) {
;     ...
;     if (MODE == 2) return fminf(1.0f + __builtin_amdgcn_exp2f(-LOG2E * v), 1e30f);
;     template <int MODE> __device__ __forceinline__ void run(const f32x4 (&acc)[2][2][4][2], const Unit& u, int wr, int wc, int fr, int fq) const {
;     ...
;         char* base = (MODE == 2) ? (char*)(O + (size_t)6 * ((size_t)MTOK * 512)) + ((size_t)(((pn - 12) * 128 + u.pm) * 8 + wid__)) * 16384
;                                  : (char*)(O + (size_t)t * ((size_t)MTOK * 512) + (size_t)u.pm * BM * 512 + (colt & 511));
;         unsigned off0 = (MODE == 2) ? (unsigned)((t__ & 63) * 16) : (unsigned)((wr * 64 + fr) * 512 + wc * 32 + 8 * fq) * 2u; asm volatile("" : "+v"(off0));
; #pragma unroll
;         for (int bj = 0; bj < 2; ++bj) {
; #pragma unroll
;             for (int ai = 0; ai < 2; ++ai)
; #pragma unroll
;                 for (int m = 0; m < 4; ++m) { const unsigned off = off0 + ((MODE == 2) ? (unsigned)(((ai * 4 + m) * 2 + bj) * 1024) : (unsigned)((ai * HALF + m * 16) * 512 + bj * HALF) * 2u);
;                     const f32x4 v0 = acc[ai][bj][m][0], v1 = acc[ai][bj][m][1];
;                     u32x4 w; w.x = cvt_pk_bf16(actf<MODE>(v0[0]), actf<MODE>(v0[1])); w.y = cvt_pk_bf16(actf<MODE>(v0[2]), actf<MODE>(v0[3]));
;                     w.z = cvt_pk_bf16(actf<MODE>(v1[0]), actf<MODE>(v1[1])); w.w = cvt_pk_bf16(actf<MODE>(v1[2]), actf<MODE>(v1[3]));
;                     *(u32x4*)(base + off) = w; }
.LBB0_403:
	v_mul_f32_e32 v12, 0xbfb8aa3b, v12
	v_mul_f32_e32 v13, 0xbfb8aa3b, v13
	v_exp_f32_e32 v12, v12
	v_exp_f32_e32 v13, v13
	v_mul_f32_e32 v14, 0xbfb8aa3b, v14
	v_mul_f32_e32 v15, 0xbfb8aa3b, v15
	v_mul_f32_e32 v8, 0xbfb8aa3b, v8
	v_mul_f32_e32 v9, 0xbfb8aa3b, v9
	v_exp_f32_e32 v14, v14
	v_exp_f32_e32 v15, v15
	v_exp_f32_e32 v8, v8
	v_exp_f32_e32 v9, v9
	v_mul_f32_e32 v10, 0xbfb8aa3b, v10
	v_mul_f32_e32 v11, 0xbfb8aa3b, v11
	v_add_f32_e32 v12, 1.0, v12
	v_add_f32_e32 v13, 1.0, v13
	v_exp_f32_e32 v10, v10
	v_exp_f32_e32 v11, v11
	v_mul_f32_e32 v76, 0xbfb8aa3b, v76
	v_mul_f32_e32 v77, 0xbfb8aa3b, v77
	v_min_f32_e32 v12, 0x7149f2ca, v12
	v_min_f32_e32 v13, 0x7149f2ca, v13
	v_exp_f32_e32 v76, v76
	v_exp_f32_e32 v77, v77
	v_cvt_pk_bf16_f32 v12, v12, v13
	v_add_f32_e32 v13, 1.0, v14
	v_add_f32_e32 v14, 1.0, v15
	v_add_f32_e32 v8, 1.0, v8
	v_add_f32_e32 v9, 1.0, v9
	v_mul_f32_e32 v78, 0xbfb8aa3b, v78
	v_mul_f32_e32 v79, 0xbfb8aa3b, v79
	v_mul_f32_e32 v72, 0xbfb8aa3b, v72
	v_mul_f32_e32 v73, 0xbfb8aa3b, v73
	v_min_f32_e32 v13, 0x7149f2ca, v13
	v_min_f32_e32 v14, 0x7149f2ca, v14
	v_min_f32_e32 v8, 0x7149f2ca, v8
	v_min_f32_e32 v9, 0x7149f2ca, v9
	v_mov_b32_e32 v142, v212
	s_lshl_b32 s60, s72, 7
	v_exp_f32_e32 v78, v78
	v_exp_f32_e32 v79, v79
	v_exp_f32_e32 v72, v72
	v_exp_f32_e32 v73, v73
	v_cvt_pk_bf16_f32 v13, v13, v14
	v_cvt_pk_bf16_f32 v14, v8, v9
	v_add_f32_e32 v8, 1.0, v10
	v_add_f32_e32 v9, 1.0, v11
	s_add_i32 s60, s60, s54
	v_readfirstlane_b32 s55, v142
	v_mul_f32_e32 v74, 0xbfb8aa3b, v74
	v_mul_f32_e32 v75, 0xbfb8aa3b, v75
	v_min_f32_e32 v8, 0x7149f2ca, v8
	v_min_f32_e32 v9, 0x7149f2ca, v9
	s_ashr_i32 s55, s55, 6
	s_lshl_b32 s54, s60, 3
	v_add_f32_e32 v76, 1.0, v76
	v_add_f32_e32 v77, 1.0, v77
	v_exp_f32_e32 v74, v74
	v_exp_f32_e32 v75, v75
	v_cvt_pk_bf16_f32 v15, v8, v9
	v_mul_f32_e32 v8, 0xbfb8aa3b, v68
	v_mul_f32_e32 v9, 0xbfb8aa3b, v69
	s_nop 0
	v_min_f32_e32 v76, 0x7149f2ca, v76
	v_min_f32_e32 v77, 0x7149f2ca, v77
	v_exp_f32_e32 v8, v8
	v_exp_f32_e32 v9, v9
	s_addk_i32 s54, 0xd000
	v_cvt_pk_bf16_f32 v76, v76, v77
	v_add_f32_e32 v77, 1.0, v78
	v_add_f32_e32 v78, 1.0, v79
	v_add_f32_e32 v72, 1.0, v72
	v_add_f32_e32 v73, 1.0, v73
	v_mul_f32_e32 v10, 0xbfb8aa3b, v70
	v_mul_f32_e32 v11, 0xbfb8aa3b, v71
	s_ashr_i32 s55, s54, 31
	v_min_f32_e32 v77, 0x7149f2ca, v77
	v_min_f32_e32 v78, 0x7149f2ca, v78
	v_min_f32_e32 v72, 0x7149f2ca, v72
	v_min_f32_e32 v73, 0x7149f2ca, v73
	v_exp_f32_e32 v10, v10
	v_exp_f32_e32 v11, v11
	s_lshl_b64 s[54:55], s[54:55], 14
	v_lshlrev_b32_e32 v142, 4, v142
	v_cvt_pk_bf16_f32 v77, v77, v78
	v_cvt_pk_bf16_f32 v78, v72, v73
	v_add_f32_e32 v72, 1.0, v74
	v_add_f32_e32 v73, 1.0, v75
	s_add_u32 s54, s33, s54
	v_and_b32_e32 v142, 0x3f0, v142
	v_and_b32_e32 v190, 7, v212
	v_lshlrev_b32_e32 v190, 4, v190
	v_and_b32_e32 v191, 0x38, v212
	v_lshl_or_b32 v190, v191, 5, v190
	v_and_b32_e32 v191, 0x1c0, v212
	v_lshl_or_b32 v142, v191, 8, v190
	v_min_f32_e32 v72, 0x7149f2ca, v72
	v_min_f32_e32 v73, 0x7149f2ca, v73
	v_add_f32_e32 v8, 1.0, v8
	v_add_f32_e32 v9, 1.0, v9
	s_addc_u32 s55, s37, s55
	v_cvt_pk_bf16_f32 v79, v72, v73
	v_add_u32_e32 v72, 0x3800, v142
	v_min_f32_e32 v8, 0x7149f2ca, v8
	v_min_f32_e32 v9, 0x7149f2ca, v9
	v_mul_f32_e32 v126, 0xbfb8aa3b, v126
	v_mul_f32_e32 v127, 0xbfb8aa3b, v127
	v_mul_f32_e32 v118, 0xbfb8aa3b, v118
	v_mul_f32_e32 v119, 0xbfb8aa3b, v119
	v_mul_f32_e32 v110, 0xbfb8aa3b, v110
	v_mul_f32_e32 v111, 0xbfb8aa3b, v111
	v_mul_f32_e32 v102, 0xbfb8aa3b, v102
	v_mul_f32_e32 v103, 0xbfb8aa3b, v103
	v_mul_f32_e32 v92, 0xbfb8aa3b, v92
	v_mul_f32_e32 v93, 0xbfb8aa3b, v93
	v_mul_f32_e32 v84, 0xbfb8aa3b, v84
	v_mul_f32_e32 v85, 0xbfb8aa3b, v85
	global_store_dwordx4 v72, v[12:15], s[54:55]
	v_cvt_pk_bf16_f32 v8, v8, v9
	v_add_f32_e32 v9, 1.0, v10
	v_add_f32_e32 v10, 1.0, v11
	v_mul_f32_e32 v11, 0xbfb8aa3b, v64
	v_mul_f32_e32 v13, 0xbfb8aa3b, v65
	v_exp_f32_e32 v126, v126
	v_exp_f32_e32 v127, v127
	v_exp_f32_e32 v118, v118
	v_exp_f32_e32 v119, v119
	v_exp_f32_e32 v110, v110
	v_exp_f32_e32 v111, v111
	v_exp_f32_e32 v102, v102
	v_exp_f32_e32 v103, v103
	v_exp_f32_e32 v92, v92
	v_exp_f32_e32 v93, v93
	v_exp_f32_e32 v84, v84
	v_exp_f32_e32 v85, v85
	v_exp_f32_e32 v11, v11
	v_exp_f32_e32 v13, v13
	v_mul_f32_e32 v128, 0xbfb8aa3b, v128
	v_mul_f32_e32 v129, 0xbfb8aa3b, v129
	v_mul_f32_e32 v122, 0xbfb8aa3b, v122
	v_mul_f32_e32 v123, 0xbfb8aa3b, v123
	v_mul_f32_e32 v120, 0xbfb8aa3b, v120
	v_mul_f32_e32 v121, 0xbfb8aa3b, v121
	v_mul_f32_e32 v114, 0xbfb8aa3b, v114
	v_mul_f32_e32 v115, 0xbfb8aa3b, v115
	v_mul_f32_e32 v112, 0xbfb8aa3b, v112
	v_mul_f32_e32 v113, 0xbfb8aa3b, v113
	v_mul_f32_e32 v106, 0xbfb8aa3b, v106
	v_mul_f32_e32 v107, 0xbfb8aa3b, v107
	v_mul_f32_e32 v104, 0xbfb8aa3b, v104
	v_mul_f32_e32 v105, 0xbfb8aa3b, v105
	v_mul_f32_e32 v98, 0xbfb8aa3b, v98
	v_mul_f32_e32 v99, 0xbfb8aa3b, v99
	v_mul_f32_e32 v94, 0xbfb8aa3b, v94
	v_mul_f32_e32 v95, 0xbfb8aa3b, v95
	v_mul_f32_e32 v88, 0xbfb8aa3b, v88
	v_mul_f32_e32 v89, 0xbfb8aa3b, v89
	v_mul_f32_e32 v86, 0xbfb8aa3b, v86
	v_mul_f32_e32 v87, 0xbfb8aa3b, v87
	v_mul_f32_e32 v80, 0xbfb8aa3b, v80
	v_mul_f32_e32 v81, 0xbfb8aa3b, v81
	v_exp_f32_e32 v128, v128
	v_exp_f32_e32 v129, v129
	v_exp_f32_e32 v122, v122
	v_exp_f32_e32 v123, v123
	v_exp_f32_e32 v120, v120
	v_exp_f32_e32 v121, v121
	v_exp_f32_e32 v114, v114
	v_exp_f32_e32 v115, v115
	v_exp_f32_e32 v112, v112
	v_exp_f32_e32 v113, v113
	v_exp_f32_e32 v106, v106
	v_exp_f32_e32 v107, v107
	v_exp_f32_e32 v104, v104
	v_exp_f32_e32 v105, v105
	v_exp_f32_e32 v98, v98
	v_exp_f32_e32 v99, v99
	v_exp_f32_e32 v94, v94
	v_exp_f32_e32 v95, v95
	v_exp_f32_e32 v88, v88
	v_exp_f32_e32 v89, v89
	v_exp_f32_e32 v86, v86
; __device__ __forceinline__ unsigned cvt_pk_bf16(float lo, float hi) { f32x2_t v = {lo, hi}; bf16x2_t b = __builtin_convertvector(v, bf16x2_t); return __builtin_bit_cast(unsigned, b); }
; template <int MODE> __device__ __forceinline__ float actf(float v) {
;     ...
;     if (MODE == 2) return fminf(1.0f + __builtin_amdgcn_exp2f(-LOG2E * v), 1e30f);
;     template <int MODE> __device__ __forceinline__ void run(const f32x4 (&acc)[2][2][4][2], const Unit& u, int wr, int wc, int fr, int fq) const {
;     ...
;         char* base = (MODE == 2) ? (char*)(O + (size_t)6 * ((size_t)MTOK * 512)) + ((size_t)(((pn - 12) * 128 + u.pm) * 8 + wid__)) * 16384
;                                  : (char*)(O + (size_t)t * ((size_t)MTOK * 512) + (size_t)u.pm * BM * 512 + (colt & 511));
;         unsigned off0 = (MODE == 2) ? (unsigned)((t__ & 63) * 16) : (unsigned)((wr * 64 + fr) * 512 + wc * 32 + 8 * fq) * 2u; asm volatile("" : "+v"(off0));
; #pragma unroll
;         for (int bj = 0; bj < 2; ++bj) {
; #pragma unroll
;             for (int ai = 0; ai < 2; ++ai)
; #pragma unroll
;                 for (int m = 0; m < 4; ++m) { const unsigned off = off0 + ((MODE == 2) ? (unsigned)(((ai * 4 + m) * 2 + bj) * 1024) : (unsigned)((ai * HALF + m * 16) * 512 + bj * HALF) * 2u);
;                     const f32x4 v0 = acc[ai][bj][m][0], v1 = acc[ai][bj][m][1];
;                     u32x4 w; w.x = cvt_pk_bf16(actf<MODE>(v0[0]), actf<MODE>(v0[1])); w.y = cvt_pk_bf16(actf<MODE>(v0[2]), actf<MODE>(v0[3]));
;                     w.z = cvt_pk_bf16(actf<MODE>(v1[0]), actf<MODE>(v1[1])); w.w = cvt_pk_bf16(actf<MODE>(v1[2]), actf<MODE>(v1[3]));
;                     *(u32x4*)(base + off) = w; }
	v_exp_f32_e32 v87, v87
	v_exp_f32_e32 v80, v80
	v_exp_f32_e32 v81, v81
	v_mul_f32_e32 v124, 0xbfb8aa3b, v124
	v_mul_f32_e32 v125, 0xbfb8aa3b, v125
	v_mul_f32_e32 v116, 0xbfb8aa3b, v116
	v_mul_f32_e32 v117, 0xbfb8aa3b, v117
	v_mul_f32_e32 v108, 0xbfb8aa3b, v108
	v_mul_f32_e32 v109, 0xbfb8aa3b, v109
	v_mul_f32_e32 v100, 0xbfb8aa3b, v100
	v_mul_f32_e32 v101, 0xbfb8aa3b, v101
	v_mul_f32_e32 v90, 0xbfb8aa3b, v90
	v_mul_f32_e32 v91, 0xbfb8aa3b, v91
	v_mul_f32_e32 v82, 0xbfb8aa3b, v82
	v_mul_f32_e32 v83, 0xbfb8aa3b, v83
	v_min_f32_e32 v9, 0x7149f2ca, v9
	v_min_f32_e32 v10, 0x7149f2ca, v10
	v_add_f32_e32 v126, 1.0, v126
	v_add_f32_e32 v127, 1.0, v127
	v_exp_f32_e32 v124, v124
	v_exp_f32_e32 v125, v125
	v_add_f32_e32 v118, 1.0, v118
	v_add_f32_e32 v119, 1.0, v119
	v_exp_f32_e32 v116, v116
	v_exp_f32_e32 v117, v117
	v_add_f32_e32 v110, 1.0, v110
	v_add_f32_e32 v111, 1.0, v111
	v_exp_f32_e32 v108, v108
	v_exp_f32_e32 v109, v109
	v_add_f32_e32 v102, 1.0, v102
	v_add_f32_e32 v103, 1.0, v103
	v_exp_f32_e32 v100, v100
	v_exp_f32_e32 v101, v101
	v_add_f32_e32 v92, 1.0, v92
	v_add_f32_e32 v93, 1.0, v93
	v_exp_f32_e32 v90, v90
	v_exp_f32_e32 v91, v91
	v_add_f32_e32 v84, 1.0, v84
	v_add_f32_e32 v85, 1.0, v85
	v_exp_f32_e32 v82, v82
	v_exp_f32_e32 v83, v83
	v_cvt_pk_bf16_f32 v9, v9, v10
	v_add_f32_e32 v10, 1.0, v11
	v_add_f32_e32 v11, 1.0, v13
	v_mul_f32_e32 v13, 0xbfb8aa3b, v66
	v_mul_f32_e32 v14, 0xbfb8aa3b, v67
	v_min_f32_e32 v126, 0x7149f2ca, v126
	v_min_f32_e32 v127, 0x7149f2ca, v127
	v_min_f32_e32 v118, 0x7149f2ca, v118
	v_min_f32_e32 v119, 0x7149f2ca, v119
	v_min_f32_e32 v110, 0x7149f2ca, v110
	v_min_f32_e32 v111, 0x7149f2ca, v111
	v_min_f32_e32 v102, 0x7149f2ca, v102
	v_min_f32_e32 v103, 0x7149f2ca, v103
	v_min_f32_e32 v92, 0x7149f2ca, v92
	v_min_f32_e32 v93, 0x7149f2ca, v93
	v_min_f32_e32 v84, 0x7149f2ca, v84
	v_min_f32_e32 v85, 0x7149f2ca, v85
	v_exp_f32_e32 v13, v13
	v_exp_f32_e32 v14, v14
	v_cvt_pk_bf16_f32 v126, v126, v127
	v_add_f32_e32 v127, 1.0, v128
	v_add_f32_e32 v128, 1.0, v129
	v_add_f32_e32 v122, 1.0, v122
	v_add_f32_e32 v123, 1.0, v123
	v_cvt_pk_bf16_f32 v118, v118, v119
	v_add_f32_e32 v119, 1.0, v120
	v_add_f32_e32 v120, 1.0, v121
	v_add_f32_e32 v114, 1.0, v114
	v_add_f32_e32 v115, 1.0, v115
	v_cvt_pk_bf16_f32 v110, v110, v111
	v_add_f32_e32 v111, 1.0, v112
	v_add_f32_e32 v112, 1.0, v113
	v_add_f32_e32 v106, 1.0, v106
	v_add_f32_e32 v107, 1.0, v107
	v_cvt_pk_bf16_f32 v102, v102, v103
	v_add_f32_e32 v103, 1.0, v104
	v_add_f32_e32 v104, 1.0, v105
	v_add_f32_e32 v98, 1.0, v98
	v_add_f32_e32 v99, 1.0, v99
	v_cvt_pk_bf16_f32 v92, v92, v93
	v_add_f32_e32 v93, 1.0, v94
	v_add_f32_e32 v94, 1.0, v95
	v_add_f32_e32 v88, 1.0, v88
	v_add_f32_e32 v89, 1.0, v89
	v_cvt_pk_bf16_f32 v84, v84, v85
	v_add_f32_e32 v85, 1.0, v86
	v_add_f32_e32 v86, 1.0, v87
	v_add_f32_e32 v80, 1.0, v80
	v_add_f32_e32 v81, 1.0, v81
	v_min_f32_e32 v127, 0x7149f2ca, v127
	v_min_f32_e32 v128, 0x7149f2ca, v128
	v_min_f32_e32 v122, 0x7149f2ca, v122
	v_min_f32_e32 v123, 0x7149f2ca, v123
	v_min_f32_e32 v119, 0x7149f2ca, v119
	v_min_f32_e32 v120, 0x7149f2ca, v120
	v_min_f32_e32 v114, 0x7149f2ca, v114
	v_min_f32_e32 v115, 0x7149f2ca, v115
	v_min_f32_e32 v111, 0x7149f2ca, v111
	v_min_f32_e32 v112, 0x7149f2ca, v112
	v_min_f32_e32 v106, 0x7149f2ca, v106
	v_min_f32_e32 v107, 0x7149f2ca, v107
	v_min_f32_e32 v103, 0x7149f2ca, v103
	v_min_f32_e32 v104, 0x7149f2ca, v104
	v_min_f32_e32 v98, 0x7149f2ca, v98
	v_min_f32_e32 v99, 0x7149f2ca, v99
	v_min_f32_e32 v93, 0x7149f2ca, v93
	v_min_f32_e32 v94, 0x7149f2ca, v94
	v_min_f32_e32 v88, 0x7149f2ca, v88
	v_min_f32_e32 v89, 0x7149f2ca, v89
	v_min_f32_e32 v85, 0x7149f2ca, v85
	v_min_f32_e32 v86, 0x7149f2ca, v86
	v_min_f32_e32 v80, 0x7149f2ca, v80
	v_min_f32_e32 v81, 0x7149f2ca, v81
	v_cvt_pk_bf16_f32 v127, v127, v128
	v_cvt_pk_bf16_f32 v128, v122, v123
	v_add_f32_e32 v122, 1.0, v124
	v_add_f32_e32 v123, 1.0, v125
	v_cvt_pk_bf16_f32 v119, v119, v120
	v_cvt_pk_bf16_f32 v120, v114, v115
	v_add_f32_e32 v114, 1.0, v116
	v_add_f32_e32 v115, 1.0, v117
	v_cvt_pk_bf16_f32 v111, v111, v112
	v_cvt_pk_bf16_f32 v112, v106, v107
	v_add_f32_e32 v106, 1.0, v108
	v_add_f32_e32 v107, 1.0, v109
	v_cvt_pk_bf16_f32 v103, v103, v104
	v_cvt_pk_bf16_f32 v104, v98, v99
	v_add_f32_e32 v98, 1.0, v100
	v_add_f32_e32 v99, 1.0, v101
	v_cvt_pk_bf16_f32 v93, v93, v94
	v_cvt_pk_bf16_f32 v94, v88, v89
	v_add_f32_e32 v88, 1.0, v90
	v_add_f32_e32 v89, 1.0, v91
	v_cvt_pk_bf16_f32 v85, v85, v86
	v_cvt_pk_bf16_f32 v86, v80, v81
	v_add_f32_e32 v80, 1.0, v82
	v_add_f32_e32 v81, 1.0, v83
	v_min_f32_e32 v10, 0x7149f2ca, v10
	v_min_f32_e32 v11, 0x7149f2ca, v11
	v_min_f32_e32 v122, 0x7149f2ca, v122
	v_min_f32_e32 v123, 0x7149f2ca, v123
	v_min_f32_e32 v114, 0x7149f2ca, v114
	v_min_f32_e32 v115, 0x7149f2ca, v115
	v_min_f32_e32 v106, 0x7149f2ca, v106
	v_min_f32_e32 v107, 0x7149f2ca, v107
	v_min_f32_e32 v98, 0x7149f2ca, v98
	v_min_f32_e32 v99, 0x7149f2ca, v99
	v_min_f32_e32 v88, 0x7149f2ca, v88
	v_min_f32_e32 v89, 0x7149f2ca, v89
	v_min_f32_e32 v80, 0x7149f2ca, v80
	v_min_f32_e32 v81, 0x7149f2ca, v81
	v_cvt_pk_bf16_f32 v10, v10, v11
	v_add_f32_e32 v11, 1.0, v13
	v_add_f32_e32 v13, 1.0, v14
	v_cvt_pk_bf16_f32 v129, v122, v123
	v_add_u32_e32 v122, 0x800, v142
	v_cvt_pk_bf16_f32 v121, v114, v115
	v_add_u32_e32 v114, 0x1000, v142
	v_cvt_pk_bf16_f32 v113, v106, v107
	v_add_u32_e32 v106, 0x1800, v142
	v_cvt_pk_bf16_f32 v105, v98, v99
	v_add_u32_e32 v98, 0x2000, v142
	v_cvt_pk_bf16_f32 v95, v88, v89
	v_add_u32_e32 v88, 0x2800, v142
	v_cvt_pk_bf16_f32 v87, v80, v81
	v_add_u32_e32 v80, 0x3000, v142
	v_min_f32_e32 v11, 0x7149f2ca, v11
	v_min_f32_e32 v13, 0x7149f2ca, v13
	global_store_dwordx4 v142, v[126:129], s[54:55]
; __device__ __forceinline__ unsigned cvt_pk_bf16(float lo, float hi) { f32x2_t v = {lo, hi}; bf16x2_t b = __builtin_convertvector(v, bf16x2_t); return __builtin_bit_cast(unsigned, b); }
; template <int MODE> __device__ __forceinline__ float actf(float v) {
;     ...
;     if (MODE == 2) return fminf(1.0f + __builtin_amdgcn_exp2f(-LOG2E * v), 1e30f);
;     template <int MODE> __device__ __forceinline__ void run(const f32x4 (&acc)[2][2][4][2], const Unit& u, int wr, int wc, int fr, int fq) const {
;     ...
;         char* base = (MODE == 2) ? (char*)(O + (size_t)6 * ((size_t)MTOK * 512)) + ((size_t)(((pn - 12) * 128 + u.pm) * 8 + wid__)) * 16384
;                                  : (char*)(O + (size_t)t * ((size_t)MTOK * 512) + (size_t)u.pm * BM * 512 + (colt & 511));
;         unsigned off0 = (MODE == 2) ? (unsigned)((t__ & 63) * 16) : (unsigned)((wr * 64 + fr) * 512 + wc * 32 + 8 * fq) * 2u; asm volatile("" : "+v"(off0));
; #pragma unroll
;         for (int bj = 0; bj < 2; ++bj) {
; #pragma unroll
;             for (int ai = 0; ai < 2; ++ai)
; #pragma unroll
;                 for (int m = 0; m < 4; ++m) { const unsigned off = off0 + ((MODE == 2) ? (unsigned)(((ai * 4 + m) * 2 + bj) * 1024) : (unsigned)((ai * HALF + m * 16) * 512 + bj * HALF) * 2u);
;                     const f32x4 v0 = acc[ai][bj][m][0], v1 = acc[ai][bj][m][1];
;                     u32x4 w; w.x = cvt_pk_bf16(actf<MODE>(v0[0]), actf<MODE>(v0[1])); w.y = cvt_pk_bf16(actf<MODE>(v0[2]), actf<MODE>(v0[3]));
;                     w.z = cvt_pk_bf16(actf<MODE>(v1[0]), actf<MODE>(v1[1])); w.w = cvt_pk_bf16(actf<MODE>(v1[2]), actf<MODE>(v1[3]));
;                     *(u32x4*)(base + off) = w; }
	global_store_dwordx4 v122, v[118:121], s[54:55]
	global_store_dwordx4 v114, v[110:113], s[54:55]
	global_store_dwordx4 v106, v[102:105], s[54:55]
	global_store_dwordx4 v98, v[92:95], s[54:55]
	global_store_dwordx4 v88, v[84:87], s[54:55]
	global_store_dwordx4 v80, v[76:79], s[54:55]
	v_add_u32_e32 v12, 0x80, v142
	v_cvt_pk_bf16_f32 v11, v11, v13
	global_store_dwordx4 v12, v[8:11], s[54:55]
	v_mul_f32_e32 v13, 0xbfb8aa3b, v57
	v_exp_f32_e32 v13, v13
	v_mul_f32_e32 v8, 0xbfb8aa3b, v60
	v_mul_f32_e32 v9, 0xbfb8aa3b, v61
	v_exp_f32_e32 v8, v8
	v_exp_f32_e32 v9, v9
	v_mul_f32_e32 v10, 0xbfb8aa3b, v62
	v_mul_f32_e32 v11, 0xbfb8aa3b, v63
	v_exp_f32_e32 v10, v10
	v_exp_f32_e32 v11, v11
	v_add_f32_e32 v8, 1.0, v8
	v_add_f32_e32 v9, 1.0, v9
	v_min_f32_e32 v8, 0x7149f2ca, v8
	v_min_f32_e32 v9, 0x7149f2ca, v9
	v_cvt_pk_bf16_f32 v8, v8, v9
	v_add_f32_e32 v9, 1.0, v10
	v_add_f32_e32 v10, 1.0, v11
	v_mul_f32_e32 v11, 0xbfb8aa3b, v56
	v_exp_f32_e32 v11, v11
	v_min_f32_e32 v9, 0x7149f2ca, v9
	v_min_f32_e32 v10, 0x7149f2ca, v10
	v_cvt_pk_bf16_f32 v9, v9, v10
	v_add_f32_e32 v10, 1.0, v11
	v_add_f32_e32 v11, 1.0, v13
	v_mul_f32_e32 v13, 0xbfb8aa3b, v58
	v_mul_f32_e32 v14, 0xbfb8aa3b, v59
	v_exp_f32_e32 v13, v13
	v_exp_f32_e32 v14, v14
	v_min_f32_e32 v10, 0x7149f2ca, v10
	v_min_f32_e32 v11, 0x7149f2ca, v11
	v_cvt_pk_bf16_f32 v10, v10, v11
	v_add_f32_e32 v11, 1.0, v13
	v_add_f32_e32 v13, 1.0, v14
	v_min_f32_e32 v11, 0x7149f2ca, v11
	v_min_f32_e32 v13, 0x7149f2ca, v13
	v_add_u32_e32 v12, 0x880, v142
	v_cvt_pk_bf16_f32 v11, v11, v13
	global_store_dwordx4 v12, v[8:11], s[54:55]
	v_mul_f32_e32 v13, 0xbfb8aa3b, v49
	v_exp_f32_e32 v13, v13
	v_mul_f32_e32 v8, 0xbfb8aa3b, v52
	v_mul_f32_e32 v9, 0xbfb8aa3b, v53
	v_exp_f32_e32 v8, v8
	v_exp_f32_e32 v9, v9
	v_mul_f32_e32 v10, 0xbfb8aa3b, v54
	v_mul_f32_e32 v11, 0xbfb8aa3b, v55
	v_exp_f32_e32 v10, v10
	v_exp_f32_e32 v11, v11
	v_add_f32_e32 v8, 1.0, v8
	v_add_f32_e32 v9, 1.0, v9
	v_min_f32_e32 v8, 0x7149f2ca, v8
	v_min_f32_e32 v9, 0x7149f2ca, v9
	v_cvt_pk_bf16_f32 v8, v8, v9
	v_add_f32_e32 v9, 1.0, v10
	v_add_f32_e32 v10, 1.0, v11
	v_mul_f32_e32 v11, 0xbfb8aa3b, v48
	v_exp_f32_e32 v11, v11
	v_min_f32_e32 v9, 0x7149f2ca, v9
	v_min_f32_e32 v10, 0x7149f2ca, v10
	v_cvt_pk_bf16_f32 v9, v9, v10
	v_add_f32_e32 v10, 1.0, v11
	v_add_f32_e32 v11, 1.0, v13
	v_mul_f32_e32 v13, 0xbfb8aa3b, v50
	v_mul_f32_e32 v14, 0xbfb8aa3b, v51
	v_exp_f32_e32 v13, v13
	v_exp_f32_e32 v14, v14
	v_min_f32_e32 v10, 0x7149f2ca, v10
	v_min_f32_e32 v11, 0x7149f2ca, v11
	v_cvt_pk_bf16_f32 v10, v10, v11
	v_add_f32_e32 v11, 1.0, v13
	v_add_f32_e32 v13, 1.0, v14
	v_min_f32_e32 v11, 0x7149f2ca, v11
	v_min_f32_e32 v13, 0x7149f2ca, v13
	v_add_u32_e32 v12, 0x1080, v142
	v_cvt_pk_bf16_f32 v11, v11, v13
	global_store_dwordx4 v12, v[8:11], s[54:55]
	v_mul_f32_e32 v13, 0xbfb8aa3b, v41
	v_exp_f32_e32 v13, v13
	v_mul_f32_e32 v8, 0xbfb8aa3b, v44
	v_mul_f32_e32 v9, 0xbfb8aa3b, v45
	v_exp_f32_e32 v8, v8
	v_exp_f32_e32 v9, v9
	v_mul_f32_e32 v10, 0xbfb8aa3b, v46
	v_mul_f32_e32 v11, 0xbfb8aa3b, v47
	v_exp_f32_e32 v10, v10
	v_exp_f32_e32 v11, v11
	v_add_f32_e32 v8, 1.0, v8
	v_add_f32_e32 v9, 1.0, v9
	v_min_f32_e32 v8, 0x7149f2ca, v8
	v_min_f32_e32 v9, 0x7149f2ca, v9
	v_cvt_pk_bf16_f32 v8, v8, v9
	v_add_f32_e32 v9, 1.0, v10
	v_add_f32_e32 v10, 1.0, v11
	v_mul_f32_e32 v11, 0xbfb8aa3b, v40
	v_exp_f32_e32 v11, v11
	v_min_f32_e32 v9, 0x7149f2ca, v9
	v_min_f32_e32 v10, 0x7149f2ca, v10
	v_cvt_pk_bf16_f32 v9, v9, v10
	v_add_f32_e32 v10, 1.0, v11
	v_add_f32_e32 v11, 1.0, v13
	v_mul_f32_e32 v13, 0xbfb8aa3b, v42
	v_mul_f32_e32 v14, 0xbfb8aa3b, v43
	v_exp_f32_e32 v13, v13
	v_exp_f32_e32 v14, v14
	v_min_f32_e32 v10, 0x7149f2ca, v10
	v_min_f32_e32 v11, 0x7149f2ca, v11
	v_cvt_pk_bf16_f32 v10, v10, v11
	v_add_f32_e32 v11, 1.0, v13
	v_add_f32_e32 v13, 1.0, v14
	v_min_f32_e32 v11, 0x7149f2ca, v11
	v_min_f32_e32 v13, 0x7149f2ca, v13
	v_add_u32_e32 v12, 0x1880, v142
	v_cvt_pk_bf16_f32 v11, v11, v13
	global_store_dwordx4 v12, v[8:11], s[54:55]
	v_mul_f32_e32 v13, 0xbfb8aa3b, v33
	v_exp_f32_e32 v13, v13
	v_mul_f32_e32 v8, 0xbfb8aa3b, v36
	v_mul_f32_e32 v9, 0xbfb8aa3b, v37
	v_exp_f32_e32 v8, v8
	v_exp_f32_e32 v9, v9
	v_mul_f32_e32 v10, 0xbfb8aa3b, v38
	v_mul_f32_e32 v11, 0xbfb8aa3b, v39
	v_exp_f32_e32 v10, v10
	v_exp_f32_e32 v11, v11
	v_add_f32_e32 v8, 1.0, v8
	v_add_f32_e32 v9, 1.0, v9
	v_min_f32_e32 v8, 0x7149f2ca, v8
; __device__ __forceinline__ unsigned cvt_pk_bf16(float lo, float hi) { f32x2_t v = {lo, hi}; bf16x2_t b = __builtin_convertvector(v, bf16x2_t); return __builtin_bit_cast(unsigned, b); }
; template <int MODE> __device__ __forceinline__ float actf(float v) {
;     ...
;     if (MODE == 2) return fminf(1.0f + __builtin_amdgcn_exp2f(-LOG2E * v), 1e30f);
;     template <int MODE> __device__ __forceinline__ void run(const f32x4 (&acc)[2][2][4][2], const Unit& u, int wr, int wc, int fr, int fq) const {
;     ...
;         char* base = (MODE == 2) ? (char*)(O + (size_t)6 * ((size_t)MTOK * 512)) + ((size_t)(((pn - 12) * 128 + u.pm) * 8 + wid__)) * 16384
;                                  : (char*)(O + (size_t)t * ((size_t)MTOK * 512) + (size_t)u.pm * BM * 512 + (colt & 511));
;         unsigned off0 = (MODE == 2) ? (unsigned)((t__ & 63) * 16) : (unsigned)((wr * 64 + fr) * 512 + wc * 32 + 8 * fq) * 2u; asm volatile("" : "+v"(off0));
; #pragma unroll
;         for (int bj = 0; bj < 2; ++bj) {
; #pragma unroll
;             for (int ai = 0; ai < 2; ++ai)
; #pragma unroll
;                 for (int m = 0; m < 4; ++m) { const unsigned off = off0 + ((MODE == 2) ? (unsigned)(((ai * 4 + m) * 2 + bj) * 1024) : (unsigned)((ai * HALF + m * 16) * 512 + bj * HALF) * 2u);
;                     const f32x4 v0 = acc[ai][bj][m][0], v1 = acc[ai][bj][m][1];
;                     u32x4 w; w.x = cvt_pk_bf16(actf<MODE>(v0[0]), actf<MODE>(v0[1])); w.y = cvt_pk_bf16(actf<MODE>(v0[2]), actf<MODE>(v0[3]));
;                     w.z = cvt_pk_bf16(actf<MODE>(v1[0]), actf<MODE>(v1[1])); w.w = cvt_pk_bf16(actf<MODE>(v1[2]), actf<MODE>(v1[3]));
;                     *(u32x4*)(base + off) = w; }
	v_min_f32_e32 v9, 0x7149f2ca, v9
	v_cvt_pk_bf16_f32 v8, v8, v9
	v_add_f32_e32 v9, 1.0, v10
	v_add_f32_e32 v10, 1.0, v11
	v_mul_f32_e32 v11, 0xbfb8aa3b, v32
	v_exp_f32_e32 v11, v11
	v_min_f32_e32 v9, 0x7149f2ca, v9
	v_min_f32_e32 v10, 0x7149f2ca, v10
	v_cvt_pk_bf16_f32 v9, v9, v10
	v_add_f32_e32 v10, 1.0, v11
	v_add_f32_e32 v11, 1.0, v13
	v_mul_f32_e32 v13, 0xbfb8aa3b, v34
	v_mul_f32_e32 v14, 0xbfb8aa3b, v35
	v_exp_f32_e32 v13, v13
	v_exp_f32_e32 v14, v14
	v_min_f32_e32 v10, 0x7149f2ca, v10
	v_min_f32_e32 v11, 0x7149f2ca, v11
	v_cvt_pk_bf16_f32 v10, v10, v11
	v_add_f32_e32 v11, 1.0, v13
	v_add_f32_e32 v13, 1.0, v14
	v_min_f32_e32 v11, 0x7149f2ca, v11
	v_min_f32_e32 v13, 0x7149f2ca, v13
	v_add_u32_e32 v12, 0x2080, v142
	v_cvt_pk_bf16_f32 v11, v11, v13
	global_store_dwordx4 v12, v[8:11], s[54:55]
	v_mul_f32_e32 v13, 0xbfb8aa3b, v25
	v_exp_f32_e32 v13, v13
	v_mul_f32_e32 v8, 0xbfb8aa3b, v28
	v_mul_f32_e32 v9, 0xbfb8aa3b, v29
	v_exp_f32_e32 v8, v8
	v_exp_f32_e32 v9, v9
	v_mul_f32_e32 v10, 0xbfb8aa3b, v30
	v_mul_f32_e32 v11, 0xbfb8aa3b, v31
	v_exp_f32_e32 v10, v10
	v_exp_f32_e32 v11, v11
	v_add_f32_e32 v8, 1.0, v8
	v_add_f32_e32 v9, 1.0, v9
	v_min_f32_e32 v8, 0x7149f2ca, v8
	v_min_f32_e32 v9, 0x7149f2ca, v9
	v_cvt_pk_bf16_f32 v8, v8, v9
	v_add_f32_e32 v9, 1.0, v10
	v_add_f32_e32 v10, 1.0, v11
	v_mul_f32_e32 v11, 0xbfb8aa3b, v24
	v_exp_f32_e32 v11, v11
	v_min_f32_e32 v9, 0x7149f2ca, v9
	v_min_f32_e32 v10, 0x7149f2ca, v10
	v_cvt_pk_bf16_f32 v9, v9, v10
	v_add_f32_e32 v10, 1.0, v11
	v_add_f32_e32 v11, 1.0, v13
	v_mul_f32_e32 v13, 0xbfb8aa3b, v26
	v_mul_f32_e32 v14, 0xbfb8aa3b, v27
	v_exp_f32_e32 v13, v13
	v_exp_f32_e32 v14, v14
	v_min_f32_e32 v10, 0x7149f2ca, v10
	v_min_f32_e32 v11, 0x7149f2ca, v11
	v_cvt_pk_bf16_f32 v10, v10, v11
	v_add_f32_e32 v11, 1.0, v13
	v_add_f32_e32 v13, 1.0, v14
	v_min_f32_e32 v11, 0x7149f2ca, v11
	v_min_f32_e32 v13, 0x7149f2ca, v13
	v_add_u32_e32 v12, 0x2880, v142
	v_cvt_pk_bf16_f32 v11, v11, v13
	global_store_dwordx4 v12, v[8:11], s[54:55]
	v_mul_f32_e32 v13, 0xbfb8aa3b, v17
	v_exp_f32_e32 v13, v13
	v_mul_f32_e32 v8, 0xbfb8aa3b, v20
	v_mul_f32_e32 v9, 0xbfb8aa3b, v21
	v_exp_f32_e32 v8, v8
	v_exp_f32_e32 v9, v9
	v_mul_f32_e32 v10, 0xbfb8aa3b, v22
	v_mul_f32_e32 v11, 0xbfb8aa3b, v23
	v_exp_f32_e32 v10, v10
	v_exp_f32_e32 v11, v11
	v_add_f32_e32 v8, 1.0, v8
	v_add_f32_e32 v9, 1.0, v9
	v_min_f32_e32 v8, 0x7149f2ca, v8
	v_min_f32_e32 v9, 0x7149f2ca, v9
	v_cvt_pk_bf16_f32 v8, v8, v9
	v_add_f32_e32 v9, 1.0, v10
	v_add_f32_e32 v10, 1.0, v11
	v_mul_f32_e32 v11, 0xbfb8aa3b, v16
	v_exp_f32_e32 v11, v11
	v_mul_f32_e32 v4, 0xbfb8aa3b, v4
	v_mul_f32_e32 v5, 0xbfb8aa3b, v5
	v_exp_f32_e32 v4, v4
	v_exp_f32_e32 v5, v5
	v_min_f32_e32 v9, 0x7149f2ca, v9
	v_min_f32_e32 v10, 0x7149f2ca, v10
	v_mul_f32_e32 v6, 0xbfb8aa3b, v6
	v_mul_f32_e32 v7, 0xbfb8aa3b, v7
	v_mul_f32_e32 v0, 0xbfb8aa3b, v0
	v_mul_f32_e32 v1, 0xbfb8aa3b, v1
	v_cvt_pk_bf16_f32 v9, v9, v10
	v_add_f32_e32 v10, 1.0, v11
	v_add_f32_e32 v11, 1.0, v13
	v_mul_f32_e32 v13, 0xbfb8aa3b, v18
	v_mul_f32_e32 v14, 0xbfb8aa3b, v19
	v_exp_f32_e32 v6, v6
	v_exp_f32_e32 v7, v7
	v_exp_f32_e32 v0, v0
	v_exp_f32_e32 v1, v1
	v_exp_f32_e32 v13, v13
	v_exp_f32_e32 v14, v14
	v_mul_f32_e32 v2, 0xbfb8aa3b, v2
	v_mul_f32_e32 v3, 0xbfb8aa3b, v3
	v_add_f32_e32 v4, 1.0, v4
	v_add_f32_e32 v5, 1.0, v5
	v_exp_f32_e32 v2, v2
	v_exp_f32_e32 v3, v3
	v_min_f32_e32 v4, 0x7149f2ca, v4
	v_min_f32_e32 v5, 0x7149f2ca, v5
	v_min_f32_e32 v10, 0x7149f2ca, v10
	v_min_f32_e32 v11, 0x7149f2ca, v11
	v_cvt_pk_bf16_f32 v4, v4, v5
	v_add_f32_e32 v5, 1.0, v6
	v_add_f32_e32 v6, 1.0, v7
	v_add_f32_e32 v0, 1.0, v0
	v_add_f32_e32 v1, 1.0, v1
	v_cvt_pk_bf16_f32 v10, v10, v11
	v_add_f32_e32 v11, 1.0, v13
	v_add_f32_e32 v13, 1.0, v14
	v_min_f32_e32 v5, 0x7149f2ca, v5
	v_min_f32_e32 v6, 0x7149f2ca, v6
	v_min_f32_e32 v0, 0x7149f2ca, v0
	v_min_f32_e32 v1, 0x7149f2ca, v1
	v_min_f32_e32 v11, 0x7149f2ca, v11
	v_min_f32_e32 v13, 0x7149f2ca, v13
	v_cvt_pk_bf16_f32 v5, v5, v6
	v_cvt_pk_bf16_f32 v6, v0, v1
	v_add_f32_e32 v0, 1.0, v2
	v_add_f32_e32 v1, 1.0, v3
	v_add_u32_e32 v12, 0x3080, v142
	v_cvt_pk_bf16_f32 v11, v11, v13
	v_min_f32_e32 v0, 0x7149f2ca, v0
	v_min_f32_e32 v1, 0x7149f2ca, v1
	global_store_dwordx4 v12, v[8:11], s[54:55]
	v_cvt_pk_bf16_f32 v7, v0, v1
	s_nop 0
	v_add_u32_e32 v8, 0x3880, v142
	global_store_dwordx4 v8, v[4:7], s[54:55]
